# s_setprio 1 of each GEMM MFMA segment issued before the load-segment wait instead of after the barrier
# speedup vs baseline: 1.0031x; 1.0026x over previous
.LBB0_67:
	s_add_u32 s34, s6, 0xfff80080
	s_addc_u32 s35, s7, -1
	s_add_i32 s53, 0, 0x10000
	s_cmp_eq_u32 s52, 28
	s_cselect_b32 s37, s25, s35
	s_cselect_b32 s36, s29, s34
	s_cselect_b32 s35, s23, s51
	s_cselect_b32 s34, s49, s50
	s_add_i32 s56, 0, 0x14000
	v_add_u32_e32 v142, s53, v187
	v_add_u32_e32 v158, s56, v187
	ds_read_b128 v[130:133], v142
	ds_read_b128 v[134:137], v142 offset:1024
	ds_read_b128 v[138:141], v142 offset:2048
	ds_read_b128 v[142:145], v142 offset:3072
	ds_read_b128 v[146:149], v158
	ds_read_b128 v[150:153], v158 offset:1024
	ds_read_b128 v[154:157], v158 offset:2048
	ds_read_b128 v[158:161], v158 offset:3072
	v_lshl_add_u64 v[184:185], s[6:7], 0, v[168:169]
	s_add_i32 m0, s43, 0xc000
	ds_read_b128 v[172:175], v199
	ds_read_b128 v[178:181], v199 offset:1024
	ds_read_b128 v[188:191], v199 offset:2048
	ds_read_b128 v[200:203], v199 offset:3072
	ds_read_b128 v[204:207], v199 offset:4096
	ds_read_b128 v[216:219], v199 offset:5120
	ds_read_b128 v[220:223], v199 offset:6144
	ds_read_b128 v[224:227], v199 offset:7168
	global_load_lds_dwordx4 v[184:185], off
	v_lshl_add_u64 v[184:185], s[6:7], 0, v[170:171]
	s_add_i32 m0, s43, 0xe000
	s_nop 0
	global_load_lds_dwordx4 v[184:185], off
	s_setprio 1
	s_waitcnt vmcnt(8) lgkmcnt(0)
	s_barrier
	v_mfma_f32_16x16x32_bf16 v[126:129], v[130:133], v[172:175], v[126:129]
	v_mfma_f32_16x16x32_bf16 v[122:125], v[138:141], v[172:175], v[122:125]
	v_mfma_f32_16x16x32_bf16 v[110:113], v[130:133], v[188:191], v[110:113]
	v_mfma_f32_16x16x32_bf16 v[106:109], v[138:141], v[188:191], v[106:109]
	v_mfma_f32_16x16x32_bf16 v[98:101], v[130:133], v[204:207], v[98:101]
	v_mfma_f32_16x16x32_bf16 v[90:93], v[138:141], v[204:207], v[90:93]
	v_mfma_f32_16x16x32_bf16 v[82:85], v[130:133], v[220:223], v[82:85]
	v_mfma_f32_16x16x32_bf16 v[74:77], v[138:141], v[220:223], v[74:77]
	v_mfma_f32_16x16x32_bf16 v[126:129], v[134:137], v[178:181], v[126:129]
	v_mfma_f32_16x16x32_bf16 v[122:125], v[142:145], v[178:181], v[122:125]
	v_mfma_f32_16x16x32_bf16 v[110:113], v[134:137], v[200:203], v[110:113]
	v_mfma_f32_16x16x32_bf16 v[106:109], v[142:145], v[200:203], v[106:109]
	v_mfma_f32_16x16x32_bf16 v[98:101], v[134:137], v[216:219], v[98:101]
	v_mfma_f32_16x16x32_bf16 v[90:93], v[142:145], v[216:219], v[90:93]
	v_mfma_f32_16x16x32_bf16 v[82:85], v[134:137], v[224:227], v[82:85]
	v_mfma_f32_16x16x32_bf16 v[74:77], v[142:145], v[224:227], v[74:77]
	v_mfma_f32_16x16x32_bf16 v[118:121], v[146:149], v[172:175], v[118:121]
	v_mfma_f32_16x16x32_bf16 v[114:117], v[154:157], v[172:175], v[114:117]
	v_mfma_f32_16x16x32_bf16 v[102:105], v[146:149], v[188:191], v[102:105]
	v_mfma_f32_16x16x32_bf16 v[94:97], v[154:157], v[188:191], v[94:97]
	v_mfma_f32_16x16x32_bf16 v[86:89], v[146:149], v[204:207], v[86:89]
	v_mfma_f32_16x16x32_bf16 v[78:81], v[154:157], v[204:207], v[78:81]
	v_mfma_f32_16x16x32_bf16 v[70:73], v[146:149], v[220:223], v[70:73]
	v_mfma_f32_16x16x32_bf16 v[66:69], v[154:157], v[220:223], v[66:69]
	v_mfma_f32_16x16x32_bf16 v[118:121], v[150:153], v[178:181], v[118:121]
	v_mfma_f32_16x16x32_bf16 v[114:117], v[158:161], v[178:181], v[114:117]
	v_mfma_f32_16x16x32_bf16 v[102:105], v[150:153], v[200:203], v[102:105]
	v_mfma_f32_16x16x32_bf16 v[94:97], v[158:161], v[200:203], v[94:97]
	v_mfma_f32_16x16x32_bf16 v[86:89], v[150:153], v[216:219], v[86:89]
	v_mfma_f32_16x16x32_bf16 v[78:81], v[158:161], v[216:219], v[78:81]
	v_mfma_f32_16x16x32_bf16 v[70:73], v[150:153], v[224:227], v[70:73]
	v_mfma_f32_16x16x32_bf16 v[66:69], v[158:161], v[224:227], v[66:69]
	s_setprio 0
	s_barrier
	s_add_i32 s53, s53, s42
	v_lshl_add_u64 v[184:185], s[34:35], 0, v[210:211]
	s_mov_b32 m0, s53
	ds_read_b128 v[172:175], v199 offset:16384
	ds_read_b128 v[178:181], v199 offset:17408
	ds_read_b128 v[188:191], v199 offset:18432
	ds_read_b128 v[200:203], v199 offset:19456
	ds_read_b128 v[204:207], v199 offset:20480
	ds_read_b128 v[216:219], v199 offset:21504
	ds_read_b128 v[220:223], v199 offset:22528
	ds_read_b128 v[224:227], v199 offset:23552
	global_load_lds_dwordx4 v[184:185], off
	s_add_i32 m0, s53, 0x2000
	s_add_u32 s54, s34, 0x80000
	v_lshl_add_u64 v[192:193], s[34:35], 0, v[162:163]
	s_addc_u32 s55, s35, 0
	s_add_i32 s53, s56, s42
	global_load_lds_dwordx4 v[192:193], off
	v_lshl_add_u64 v[196:197], s[54:55], 0, v[210:211]
	s_mov_b32 m0, s53
	v_lshl_add_u64 v[208:209], s[36:37], 0, v[164:165]
	global_load_lds_dwordx4 v[196:197], off
	v_lshl_add_u64 v[196:197], s[54:55], 0, v[162:163]
	s_add_i32 m0, s53, 0x2000
	s_nop 0
	global_load_lds_dwordx4 v[196:197], off
	v_lshl_add_u64 v[196:197], s[36:37], 0, v[166:167]
	s_mov_b32 m0, s43
	s_nop 0
	global_load_lds_dwordx4 v[196:197], off
	s_mov_b32 m0, s44
	s_nop 0
	global_load_lds_dwordx4 v[208:209], off
	s_setprio 1
	s_waitcnt vmcnt(8) lgkmcnt(0)
	s_barrier
	v_mfma_f32_16x16x32_bf16 v[62:65], v[130:133], v[172:175], v[62:65]
	v_mfma_f32_16x16x32_bf16 v[58:61], v[138:141], v[172:175], v[58:61]
	v_mfma_f32_16x16x32_bf16 v[50:53], v[130:133], v[188:191], v[50:53]
	v_mfma_f32_16x16x32_bf16 v[42:45], v[138:141], v[188:191], v[42:45]
	v_mfma_f32_16x16x32_bf16 v[34:37], v[130:133], v[204:207], v[34:37]
	v_mfma_f32_16x16x32_bf16 v[26:29], v[138:141], v[204:207], v[26:29]
	v_mfma_f32_16x16x32_bf16 v[14:17], v[130:133], v[220:223], v[14:17]
	v_mfma_f32_16x16x32_bf16 v[10:13], v[138:141], v[220:223], v[10:13]
	v_mfma_f32_16x16x32_bf16 v[62:65], v[134:137], v[178:181], v[62:65]
	v_mfma_f32_16x16x32_bf16 v[58:61], v[142:145], v[178:181], v[58:61]
	v_mfma_f32_16x16x32_bf16 v[50:53], v[134:137], v[200:203], v[50:53]
	v_mfma_f32_16x16x32_bf16 v[42:45], v[142:145], v[200:203], v[42:45]
	v_mfma_f32_16x16x32_bf16 v[34:37], v[134:137], v[216:219], v[34:37]
	v_mfma_f32_16x16x32_bf16 v[26:29], v[142:145], v[216:219], v[26:29]
	v_mfma_f32_16x16x32_bf16 v[14:17], v[134:137], v[224:227], v[14:17]
	v_mfma_f32_16x16x32_bf16 v[10:13], v[142:145], v[224:227], v[10:13]
	v_mfma_f32_16x16x32_bf16 v[54:57], v[146:149], v[172:175], v[54:57]
	v_mfma_f32_16x16x32_bf16 v[46:49], v[154:157], v[172:175], v[46:49]
	v_mfma_f32_16x16x32_bf16 v[38:41], v[146:149], v[188:191], v[38:41]
	v_mfma_f32_16x16x32_bf16 v[30:33], v[154:157], v[188:191], v[30:33]
	v_mfma_f32_16x16x32_bf16 v[22:25], v[146:149], v[204:207], v[22:25]
	v_mfma_f32_16x16x32_bf16 v[18:21], v[154:157], v[204:207], v[18:21]
	v_mfma_f32_16x16x32_bf16 v[6:9], v[146:149], v[220:223], v[6:9]
	v_mfma_f32_16x16x32_bf16 v[2:5], v[154:157], v[220:223], v[2:5]
	v_mfma_f32_16x16x32_bf16 v[54:57], v[150:153], v[178:181], v[54:57]
	v_mfma_f32_16x16x32_bf16 v[46:49], v[158:161], v[178:181], v[46:49]
	v_mfma_f32_16x16x32_bf16 v[38:41], v[150:153], v[200:203], v[38:41]
	v_mfma_f32_16x16x32_bf16 v[30:33], v[158:161], v[200:203], v[30:33]
	v_mfma_f32_16x16x32_bf16 v[22:25], v[150:153], v[216:219], v[22:25]
	v_mfma_f32_16x16x32_bf16 v[18:21], v[158:161], v[216:219], v[18:21]
	v_mfma_f32_16x16x32_bf16 v[6:9], v[150:153], v[224:227], v[6:9]
	v_mfma_f32_16x16x32_bf16 v[2:5], v[158:161], v[224:227], v[2:5]
	s_setprio 0
	s_barrier
	s_add_i32 s53, 0, 0x18000
	s_add_i32 s54, 0, 0x1c000
	v_add_u32_e32 v142, s53, v187
	v_add_u32_e32 v158, s54, v187
	ds_read_b128 v[130:133], v142
	ds_read_b128 v[134:137], v142 offset:1024
	ds_read_b128 v[138:141], v142 offset:2048
	ds_read_b128 v[142:145], v142 offset:3072
	ds_read_b128 v[146:149], v158
	ds_read_b128 v[150:153], v158 offset:1024
	ds_read_b128 v[154:157], v158 offset:2048
	ds_read_b128 v[158:161], v158 offset:3072
	s_add_u32 s36, s36, 0x80000
	s_addc_u32 s37, s37, 0
	s_mov_b32 m0, s45
	v_lshl_add_u64 v[212:213], s[36:37], 0, v[166:167]
	ds_read_b128 v[172:175], v199 offset:32768
	ds_read_b128 v[178:181], v199 offset:33792
	ds_read_b128 v[188:191], v199 offset:34816
	ds_read_b128 v[200:203], v199 offset:35840
	ds_read_b128 v[204:207], v199 offset:36864
	ds_read_b128 v[216:219], v199 offset:37888
	ds_read_b128 v[220:223], v199 offset:38912
	ds_read_b128 v[224:227], v199 offset:39936
	global_load_lds_dwordx4 v[212:213], off
	v_lshl_add_u64 v[212:213], s[36:37], 0, v[164:165]
	s_mov_b32 m0, s46
	s_nop 0
	global_load_lds_dwordx4 v[212:213], off
	s_setprio 1
	s_waitcnt vmcnt(8) lgkmcnt(0)
	s_barrier
	v_mfma_f32_16x16x32_bf16 v[126:129], v[130:133], v[172:175], v[126:129]
	v_mfma_f32_16x16x32_bf16 v[122:125], v[138:141], v[172:175], v[122:125]
	v_mfma_f32_16x16x32_bf16 v[110:113], v[130:133], v[188:191], v[110:113]
	v_mfma_f32_16x16x32_bf16 v[106:109], v[138:141], v[188:191], v[106:109]
	v_mfma_f32_16x16x32_bf16 v[98:101], v[130:133], v[204:207], v[98:101]
	v_mfma_f32_16x16x32_bf16 v[90:93], v[138:141], v[204:207], v[90:93]
	v_mfma_f32_16x16x32_bf16 v[82:85], v[130:133], v[220:223], v[82:85]
	v_mfma_f32_16x16x32_bf16 v[74:77], v[138:141], v[220:223], v[74:77]
	v_mfma_f32_16x16x32_bf16 v[126:129], v[134:137], v[178:181], v[126:129]
	v_mfma_f32_16x16x32_bf16 v[122:125], v[142:145], v[178:181], v[122:125]
	v_mfma_f32_16x16x32_bf16 v[110:113], v[134:137], v[200:203], v[110:113]
	v_mfma_f32_16x16x32_bf16 v[106:109], v[142:145], v[200:203], v[106:109]
	v_mfma_f32_16x16x32_bf16 v[98:101], v[134:137], v[216:219], v[98:101]
	v_mfma_f32_16x16x32_bf16 v[90:93], v[142:145], v[216:219], v[90:93]
	v_mfma_f32_16x16x32_bf16 v[82:85], v[134:137], v[224:227], v[82:85]
	v_mfma_f32_16x16x32_bf16 v[74:77], v[142:145], v[224:227], v[74:77]
	v_mfma_f32_16x16x32_bf16 v[118:121], v[146:149], v[172:175], v[118:121]
	v_mfma_f32_16x16x32_bf16 v[114:117], v[154:157], v[172:175], v[114:117]
	v_mfma_f32_16x16x32_bf16 v[102:105], v[146:149], v[188:191], v[102:105]
	v_mfma_f32_16x16x32_bf16 v[94:97], v[154:157], v[188:191], v[94:97]
	v_mfma_f32_16x16x32_bf16 v[86:89], v[146:149], v[204:207], v[86:89]
	v_mfma_f32_16x16x32_bf16 v[78:81], v[154:157], v[204:207], v[78:81]
	v_mfma_f32_16x16x32_bf16 v[70:73], v[146:149], v[220:223], v[70:73]
	v_mfma_f32_16x16x32_bf16 v[66:69], v[154:157], v[220:223], v[66:69]
	v_mfma_f32_16x16x32_bf16 v[118:121], v[150:153], v[178:181], v[118:121]
	v_mfma_f32_16x16x32_bf16 v[114:117], v[158:161], v[178:181], v[114:117]
	v_mfma_f32_16x16x32_bf16 v[102:105], v[150:153], v[200:203], v[102:105]
	v_mfma_f32_16x16x32_bf16 v[94:97], v[158:161], v[200:203], v[94:97]
	v_mfma_f32_16x16x32_bf16 v[86:89], v[150:153], v[216:219], v[86:89]
	v_mfma_f32_16x16x32_bf16 v[78:81], v[158:161], v[216:219], v[78:81]
	v_mfma_f32_16x16x32_bf16 v[70:73], v[150:153], v[224:227], v[70:73]
	v_mfma_f32_16x16x32_bf16 v[66:69], v[158:161], v[224:227], v[66:69]
	s_setprio 0
	s_barrier
	s_add_i32 s36, s53, s42
	v_lshl_add_u64 v[184:185], v[184:185], 0, s[64:65]
	s_mov_b32 m0, s36
	ds_read_b128 v[172:175], v199 offset:49152
	ds_read_b128 v[178:181], v199 offset:50176
	ds_read_b128 v[188:191], v199 offset:51200
	ds_read_b128 v[200:203], v199 offset:52224
	ds_read_b128 v[204:207], v199 offset:53248
	ds_read_b128 v[216:219], v199 offset:54272
	ds_read_b128 v[220:223], v199 offset:55296
	ds_read_b128 v[224:227], v199 offset:56320
	global_load_lds_dwordx4 v[184:185], off
	s_add_i32 m0, s36, 0x2000
	s_add_u32 s34, s34, 0x80080
	v_lshl_add_u64 v[184:185], v[192:193], 0, s[64:65]
	s_addc_u32 s35, s35, 0
	s_add_i32 s36, s54, s42
	global_load_lds_dwordx4 v[184:185], off
	v_lshl_add_u64 v[184:185], s[34:35], 0, v[210:211]
	s_mov_b32 m0, s36
	s_nop 0
	global_load_lds_dwordx4 v[184:185], off
	v_lshl_add_u64 v[184:185], s[34:35], 0, v[162:163]
	s_add_i32 m0, s36, 0x2000
	s_nop 0
	global_load_lds_dwordx4 v[184:185], off
	v_lshl_add_u64 v[184:185], v[196:197], 0, s[64:65]
	s_mov_b32 m0, s47
	s_nop 0
	global_load_lds_dwordx4 v[184:185], off
	v_lshl_add_u64 v[184:185], v[208:209], 0, s[64:65]
	s_mov_b32 m0, s48
	s_nop 0
	global_load_lds_dwordx4 v[184:185], off
	s_setprio 1
	s_waitcnt vmcnt(8) lgkmcnt(0)
	s_barrier
	v_mfma_f32_16x16x32_bf16 v[62:65], v[130:133], v[172:175], v[62:65]
	v_mfma_f32_16x16x32_bf16 v[58:61], v[138:141], v[172:175], v[58:61]
	v_mfma_f32_16x16x32_bf16 v[50:53], v[130:133], v[188:191], v[50:53]
	v_mfma_f32_16x16x32_bf16 v[42:45], v[138:141], v[188:191], v[42:45]
	v_mfma_f32_16x16x32_bf16 v[34:37], v[130:133], v[204:207], v[34:37]
	v_mfma_f32_16x16x32_bf16 v[26:29], v[138:141], v[204:207], v[26:29]
	v_mfma_f32_16x16x32_bf16 v[14:17], v[130:133], v[220:223], v[14:17]
	v_mfma_f32_16x16x32_bf16 v[10:13], v[138:141], v[220:223], v[10:13]
	v_mfma_f32_16x16x32_bf16 v[62:65], v[134:137], v[178:181], v[62:65]
	v_mfma_f32_16x16x32_bf16 v[58:61], v[142:145], v[178:181], v[58:61]
	v_mfma_f32_16x16x32_bf16 v[50:53], v[134:137], v[200:203], v[50:53]
	v_mfma_f32_16x16x32_bf16 v[42:45], v[142:145], v[200:203], v[42:45]
	v_mfma_f32_16x16x32_bf16 v[34:37], v[134:137], v[216:219], v[34:37]
	v_mfma_f32_16x16x32_bf16 v[26:29], v[142:145], v[216:219], v[26:29]
	v_mfma_f32_16x16x32_bf16 v[14:17], v[134:137], v[224:227], v[14:17]
	v_mfma_f32_16x16x32_bf16 v[10:13], v[142:145], v[224:227], v[10:13]
	v_mfma_f32_16x16x32_bf16 v[54:57], v[146:149], v[172:175], v[54:57]
	v_mfma_f32_16x16x32_bf16 v[46:49], v[154:157], v[172:175], v[46:49]
	v_mfma_f32_16x16x32_bf16 v[38:41], v[146:149], v[188:191], v[38:41]
	v_mfma_f32_16x16x32_bf16 v[30:33], v[154:157], v[188:191], v[30:33]
	v_mfma_f32_16x16x32_bf16 v[22:25], v[146:149], v[204:207], v[22:25]
	v_mfma_f32_16x16x32_bf16 v[18:21], v[154:157], v[204:207], v[18:21]
	v_mfma_f32_16x16x32_bf16 v[6:9], v[146:149], v[220:223], v[6:9]
	v_mfma_f32_16x16x32_bf16 v[2:5], v[154:157], v[220:223], v[2:5]
	v_mfma_f32_16x16x32_bf16 v[54:57], v[150:153], v[178:181], v[54:57]
	v_mfma_f32_16x16x32_bf16 v[46:49], v[158:161], v[178:181], v[46:49]
	v_mfma_f32_16x16x32_bf16 v[38:41], v[150:153], v[200:203], v[38:41]
	v_mfma_f32_16x16x32_bf16 v[30:33], v[158:161], v[200:203], v[30:33]
	v_mfma_f32_16x16x32_bf16 v[22:25], v[150:153], v[216:219], v[22:25]
	v_mfma_f32_16x16x32_bf16 v[18:21], v[158:161], v[216:219], v[18:21]
	v_mfma_f32_16x16x32_bf16 v[6:9], v[150:153], v[224:227], v[6:9]
	v_mfma_f32_16x16x32_bf16 v[2:5], v[158:161], v[224:227], v[2:5]
	s_setprio 0
	s_barrier
	s_add_i32 s52, s52, 2
	s_add_u32 s6, s6, 0x100
	s_addc_u32 s7, s7, 0
	s_add_u32 s50, s50, 0x100
	s_addc_u32 s51, s51, 0
	s_cmp_gt_u32 s52, 29
	s_cbranch_scc0 .LBB0_67
	s_and_b64 vcc, exec, s[18:19]
	s_cbranch_vccz .LBB0_70
	s_barrier

.LBB0_116:
	s_add_u32 s30, s6, 0xfff80080
	s_addc_u32 s31, s7, -1
	s_add_i32 s52, 0, 0x10000
	s_cmp_eq_u32 s51, 28
	s_cselect_b32 s35, s23, s31
	s_cselect_b32 s34, s28, s30
	s_cselect_b32 s31, s21, s50
	s_cselect_b32 s30, s29, s49
	s_add_i32 s54, 0, 0x14000
	v_add_u32_e32 v78, s52, v240
	v_add_u32_e32 v98, s54, v240
	ds_read_b128 v[66:69], v78
	ds_read_b128 v[70:73], v78 offset:1024
	ds_read_b128 v[74:77], v78 offset:2048
	ds_read_b128 v[78:81], v78 offset:3072
	ds_read_b128 v[82:85], v98
	ds_read_b128 v[86:89], v98 offset:1024
	ds_read_b128 v[90:93], v98 offset:2048
	ds_read_b128 v[98:101], v98 offset:3072
	v_lshl_add_u64 v[212:213], s[6:7], 0, v[182:183]
	s_add_i32 m0, s37, 0xc000
	ds_read_b128 v[186:189], v241
	ds_read_b128 v[190:193], v241 offset:1024
	ds_read_b128 v[194:197], v241 offset:2048
	ds_read_b128 v[198:201], v241 offset:3072
	ds_read_b128 v[202:205], v241 offset:4096
	ds_read_b128 v[206:209], v241 offset:5120
	ds_read_b128 v[216:219], v241 offset:6144
	ds_read_b128 v[220:223], v241 offset:7168
	global_load_lds_dwordx4 v[212:213], off
	v_lshl_add_u64 v[212:213], s[6:7], 0, v[184:185]
	s_add_i32 m0, s37, 0xe000
	s_nop 0
	global_load_lds_dwordx4 v[212:213], off
	s_setprio 1
	s_waitcnt vmcnt(8) lgkmcnt(0)
	s_barrier
	v_mfma_f32_16x16x32_bf16 v[158:161], v[66:69], v[186:189], v[158:161]
	v_mfma_f32_16x16x32_bf16 v[154:157], v[74:77], v[186:189], v[154:157]
	v_mfma_f32_16x16x32_bf16 v[142:145], v[66:69], v[194:197], v[142:145]
	v_mfma_f32_16x16x32_bf16 v[138:141], v[74:77], v[194:197], v[138:141]
	v_mfma_f32_16x16x32_bf16 v[126:129], v[66:69], v[202:205], v[126:129]
	v_mfma_f32_16x16x32_bf16 v[122:125], v[74:77], v[202:205], v[122:125]
	v_mfma_f32_16x16x32_bf16 v[110:113], v[66:69], v[216:219], v[110:113]
	v_mfma_f32_16x16x32_bf16 v[106:109], v[74:77], v[216:219], v[106:109]
	v_mfma_f32_16x16x32_bf16 v[158:161], v[70:73], v[190:193], v[158:161]
	v_mfma_f32_16x16x32_bf16 v[154:157], v[78:81], v[190:193], v[154:157]
	v_mfma_f32_16x16x32_bf16 v[142:145], v[70:73], v[198:201], v[142:145]
	v_mfma_f32_16x16x32_bf16 v[138:141], v[78:81], v[198:201], v[138:141]
	v_mfma_f32_16x16x32_bf16 v[126:129], v[70:73], v[206:209], v[126:129]
	v_mfma_f32_16x16x32_bf16 v[122:125], v[78:81], v[206:209], v[122:125]
	v_mfma_f32_16x16x32_bf16 v[110:113], v[70:73], v[220:223], v[110:113]
	v_mfma_f32_16x16x32_bf16 v[106:109], v[78:81], v[220:223], v[106:109]
	v_mfma_f32_16x16x32_bf16 v[150:153], v[82:85], v[186:189], v[150:153]
	v_mfma_f32_16x16x32_bf16 v[146:149], v[90:93], v[186:189], v[146:149]
	v_mfma_f32_16x16x32_bf16 v[134:137], v[82:85], v[194:197], v[134:137]
	v_mfma_f32_16x16x32_bf16 v[130:133], v[90:93], v[194:197], v[130:133]
	v_mfma_f32_16x16x32_bf16 v[118:121], v[82:85], v[202:205], v[118:121]
	v_mfma_f32_16x16x32_bf16 v[114:117], v[90:93], v[202:205], v[114:117]
	v_mfma_f32_16x16x32_bf16 v[102:105], v[82:85], v[216:219], v[102:105]
	v_mfma_f32_16x16x32_bf16 v[94:97], v[90:93], v[216:219], v[94:97]
	v_mfma_f32_16x16x32_bf16 v[150:153], v[86:89], v[190:193], v[150:153]
	v_mfma_f32_16x16x32_bf16 v[146:149], v[98:101], v[190:193], v[146:149]
	v_mfma_f32_16x16x32_bf16 v[134:137], v[86:89], v[198:201], v[134:137]
	v_mfma_f32_16x16x32_bf16 v[130:133], v[98:101], v[198:201], v[130:133]
	v_mfma_f32_16x16x32_bf16 v[118:121], v[86:89], v[206:209], v[118:121]
	v_mfma_f32_16x16x32_bf16 v[114:117], v[98:101], v[206:209], v[114:117]
	v_mfma_f32_16x16x32_bf16 v[102:105], v[86:89], v[220:223], v[102:105]
	v_mfma_f32_16x16x32_bf16 v[94:97], v[98:101], v[220:223], v[94:97]
	s_setprio 0
	s_barrier
	s_add_i32 s52, s52, s36
	v_lshl_add_u64 v[212:213], s[30:31], 0, v[166:167]
	s_mov_b32 m0, s52
	ds_read_b128 v[186:189], v241 offset:16384
	ds_read_b128 v[190:193], v241 offset:17408
	ds_read_b128 v[194:197], v241 offset:18432
	ds_read_b128 v[198:201], v241 offset:19456
	ds_read_b128 v[202:205], v241 offset:20480
	ds_read_b128 v[206:209], v241 offset:21504
	ds_read_b128 v[216:219], v241 offset:22528
	ds_read_b128 v[220:223], v241 offset:23552
	global_load_lds_dwordx4 v[212:213], off
	s_add_i32 m0, s52, 0x2000
	s_add_u32 s52, s30, 0x80000
	v_lshl_add_u64 v[214:215], s[30:31], 0, v[162:163]
	s_addc_u32 s53, s31, 0
	s_add_i32 s54, s54, s36
	global_load_lds_dwordx4 v[214:215], off
	v_lshl_add_u64 v[224:225], s[52:53], 0, v[166:167]
	s_mov_b32 m0, s54
	v_lshl_add_u64 v[226:227], s[34:35], 0, v[164:165]
	global_load_lds_dwordx4 v[224:225], off
	v_lshl_add_u64 v[224:225], s[52:53], 0, v[162:163]
	s_add_i32 m0, s54, 0x2000
	s_nop 0
	global_load_lds_dwordx4 v[224:225], off
	v_lshl_add_u64 v[224:225], s[34:35], 0, v[168:169]
	s_mov_b32 m0, s37
	s_nop 0
	global_load_lds_dwordx4 v[224:225], off
	s_mov_b32 m0, s42
	s_nop 0
	global_load_lds_dwordx4 v[226:227], off
	s_setprio 1
	s_waitcnt vmcnt(8) lgkmcnt(0)
	s_barrier
	v_mfma_f32_16x16x32_bf16 v[62:65], v[66:69], v[186:189], v[62:65]
	v_mfma_f32_16x16x32_bf16 v[58:61], v[74:77], v[186:189], v[58:61]
	v_mfma_f32_16x16x32_bf16 v[46:49], v[66:69], v[194:197], v[46:49]
	v_mfma_f32_16x16x32_bf16 v[42:45], v[74:77], v[194:197], v[42:45]
	v_mfma_f32_16x16x32_bf16 v[30:33], v[66:69], v[202:205], v[30:33]
	v_mfma_f32_16x16x32_bf16 v[26:29], v[74:77], v[202:205], v[26:29]
	v_mfma_f32_16x16x32_bf16 v[14:17], v[66:69], v[216:219], v[14:17]
	v_mfma_f32_16x16x32_bf16 v[10:13], v[74:77], v[216:219], v[10:13]
	v_mfma_f32_16x16x32_bf16 v[62:65], v[70:73], v[190:193], v[62:65]
	v_mfma_f32_16x16x32_bf16 v[58:61], v[78:81], v[190:193], v[58:61]
	v_mfma_f32_16x16x32_bf16 v[46:49], v[70:73], v[198:201], v[46:49]
	v_mfma_f32_16x16x32_bf16 v[42:45], v[78:81], v[198:201], v[42:45]
	v_mfma_f32_16x16x32_bf16 v[30:33], v[70:73], v[206:209], v[30:33]
	v_mfma_f32_16x16x32_bf16 v[26:29], v[78:81], v[206:209], v[26:29]
	v_mfma_f32_16x16x32_bf16 v[14:17], v[70:73], v[220:223], v[14:17]
	v_mfma_f32_16x16x32_bf16 v[10:13], v[78:81], v[220:223], v[10:13]
	v_mfma_f32_16x16x32_bf16 v[54:57], v[82:85], v[186:189], v[54:57]
	v_mfma_f32_16x16x32_bf16 v[50:53], v[90:93], v[186:189], v[50:53]
	v_mfma_f32_16x16x32_bf16 v[38:41], v[82:85], v[194:197], v[38:41]
	v_mfma_f32_16x16x32_bf16 v[34:37], v[90:93], v[194:197], v[34:37]
	v_mfma_f32_16x16x32_bf16 v[22:25], v[82:85], v[202:205], v[22:25]
	v_mfma_f32_16x16x32_bf16 v[18:21], v[90:93], v[202:205], v[18:21]
	v_mfma_f32_16x16x32_bf16 v[6:9], v[82:85], v[216:219], v[6:9]
	v_mfma_f32_16x16x32_bf16 v[2:5], v[90:93], v[216:219], v[2:5]
	v_mfma_f32_16x16x32_bf16 v[54:57], v[86:89], v[190:193], v[54:57]
	v_mfma_f32_16x16x32_bf16 v[50:53], v[98:101], v[190:193], v[50:53]
	v_mfma_f32_16x16x32_bf16 v[38:41], v[86:89], v[198:201], v[38:41]
	v_mfma_f32_16x16x32_bf16 v[34:37], v[98:101], v[198:201], v[34:37]
	v_mfma_f32_16x16x32_bf16 v[22:25], v[86:89], v[206:209], v[22:25]
	v_mfma_f32_16x16x32_bf16 v[18:21], v[98:101], v[206:209], v[18:21]
	v_mfma_f32_16x16x32_bf16 v[6:9], v[86:89], v[220:223], v[6:9]
	v_mfma_f32_16x16x32_bf16 v[2:5], v[98:101], v[220:223], v[2:5]
	s_setprio 0
	s_barrier
	s_add_i32 s52, 0, 0x18000
	s_add_i32 s53, 0, 0x1c000
	v_add_u32_e32 v78, s52, v240
	v_add_u32_e32 v98, s53, v240
	ds_read_b128 v[66:69], v78
	ds_read_b128 v[70:73], v78 offset:1024
	ds_read_b128 v[74:77], v78 offset:2048
	ds_read_b128 v[78:81], v78 offset:3072
	ds_read_b128 v[82:85], v98
	ds_read_b128 v[86:89], v98 offset:1024
	ds_read_b128 v[90:93], v98 offset:2048
	ds_read_b128 v[98:101], v98 offset:3072
	s_add_u32 s34, s34, 0x80000
	s_addc_u32 s35, s35, 0
	s_mov_b32 m0, s43
	v_lshl_add_u64 v[228:229], s[34:35], 0, v[168:169]
	ds_read_b128 v[186:189], v241 offset:32768
	ds_read_b128 v[190:193], v241 offset:33792
	ds_read_b128 v[194:197], v241 offset:34816
	ds_read_b128 v[198:201], v241 offset:35840
	ds_read_b128 v[202:205], v241 offset:36864
	ds_read_b128 v[206:209], v241 offset:37888
	ds_read_b128 v[216:219], v241 offset:38912
	ds_read_b128 v[220:223], v241 offset:39936
	global_load_lds_dwordx4 v[228:229], off
	v_lshl_add_u64 v[228:229], s[34:35], 0, v[164:165]
	s_mov_b32 m0, s44
	s_nop 0
	global_load_lds_dwordx4 v[228:229], off
	s_setprio 1
	s_waitcnt vmcnt(8) lgkmcnt(0)
	s_barrier
	v_mfma_f32_16x16x32_bf16 v[158:161], v[66:69], v[186:189], v[158:161]
	v_mfma_f32_16x16x32_bf16 v[154:157], v[74:77], v[186:189], v[154:157]
	v_mfma_f32_16x16x32_bf16 v[142:145], v[66:69], v[194:197], v[142:145]
	v_mfma_f32_16x16x32_bf16 v[138:141], v[74:77], v[194:197], v[138:141]
	v_mfma_f32_16x16x32_bf16 v[126:129], v[66:69], v[202:205], v[126:129]
	v_mfma_f32_16x16x32_bf16 v[122:125], v[74:77], v[202:205], v[122:125]
	v_mfma_f32_16x16x32_bf16 v[110:113], v[66:69], v[216:219], v[110:113]
	v_mfma_f32_16x16x32_bf16 v[106:109], v[74:77], v[216:219], v[106:109]
	v_mfma_f32_16x16x32_bf16 v[158:161], v[70:73], v[190:193], v[158:161]
	v_mfma_f32_16x16x32_bf16 v[154:157], v[78:81], v[190:193], v[154:157]
	v_mfma_f32_16x16x32_bf16 v[142:145], v[70:73], v[198:201], v[142:145]
	v_mfma_f32_16x16x32_bf16 v[138:141], v[78:81], v[198:201], v[138:141]
	v_mfma_f32_16x16x32_bf16 v[126:129], v[70:73], v[206:209], v[126:129]
	v_mfma_f32_16x16x32_bf16 v[122:125], v[78:81], v[206:209], v[122:125]
	v_mfma_f32_16x16x32_bf16 v[110:113], v[70:73], v[220:223], v[110:113]
	v_mfma_f32_16x16x32_bf16 v[106:109], v[78:81], v[220:223], v[106:109]
	v_mfma_f32_16x16x32_bf16 v[150:153], v[82:85], v[186:189], v[150:153]
	v_mfma_f32_16x16x32_bf16 v[146:149], v[90:93], v[186:189], v[146:149]
	v_mfma_f32_16x16x32_bf16 v[134:137], v[82:85], v[194:197], v[134:137]
	v_mfma_f32_16x16x32_bf16 v[130:133], v[90:93], v[194:197], v[130:133]
	v_mfma_f32_16x16x32_bf16 v[118:121], v[82:85], v[202:205], v[118:121]
	v_mfma_f32_16x16x32_bf16 v[114:117], v[90:93], v[202:205], v[114:117]
	v_mfma_f32_16x16x32_bf16 v[102:105], v[82:85], v[216:219], v[102:105]
	v_mfma_f32_16x16x32_bf16 v[94:97], v[90:93], v[216:219], v[94:97]
	v_mfma_f32_16x16x32_bf16 v[150:153], v[86:89], v[190:193], v[150:153]
	v_mfma_f32_16x16x32_bf16 v[146:149], v[98:101], v[190:193], v[146:149]
	v_mfma_f32_16x16x32_bf16 v[134:137], v[86:89], v[198:201], v[134:137]
	v_mfma_f32_16x16x32_bf16 v[130:133], v[98:101], v[198:201], v[130:133]
	v_mfma_f32_16x16x32_bf16 v[118:121], v[86:89], v[206:209], v[118:121]
	v_mfma_f32_16x16x32_bf16 v[114:117], v[98:101], v[206:209], v[114:117]
	v_mfma_f32_16x16x32_bf16 v[102:105], v[86:89], v[220:223], v[102:105]
	v_mfma_f32_16x16x32_bf16 v[94:97], v[98:101], v[220:223], v[94:97]
	s_setprio 0
	s_barrier
	s_add_i32 s34, s52, s36
	v_lshl_add_u64 v[212:213], v[212:213], 0, s[64:65]
	s_mov_b32 m0, s34
	ds_read_b128 v[186:189], v241 offset:49152
	ds_read_b128 v[190:193], v241 offset:50176
	ds_read_b128 v[194:197], v241 offset:51200
	ds_read_b128 v[198:201], v241 offset:52224
	ds_read_b128 v[202:205], v241 offset:53248
	ds_read_b128 v[206:209], v241 offset:54272
	ds_read_b128 v[216:219], v241 offset:55296
	ds_read_b128 v[220:223], v241 offset:56320
	global_load_lds_dwordx4 v[212:213], off
	s_add_i32 m0, s34, 0x2000
	s_add_u32 s30, s30, 0x80080
	v_lshl_add_u64 v[212:213], v[214:215], 0, s[64:65]
	s_addc_u32 s31, s31, 0
	s_add_i32 s34, s53, s36
	global_load_lds_dwordx4 v[212:213], off
	v_lshl_add_u64 v[212:213], s[30:31], 0, v[166:167]
	s_mov_b32 m0, s34
	s_nop 0
	global_load_lds_dwordx4 v[212:213], off
	v_lshl_add_u64 v[212:213], s[30:31], 0, v[162:163]
	s_add_i32 m0, s34, 0x2000
	s_nop 0
	global_load_lds_dwordx4 v[212:213], off
	v_lshl_add_u64 v[212:213], v[224:225], 0, s[64:65]
	s_mov_b32 m0, s46
	s_nop 0
	global_load_lds_dwordx4 v[212:213], off
	v_lshl_add_u64 v[212:213], v[226:227], 0, s[64:65]
	s_mov_b32 m0, s47
	s_nop 0
	global_load_lds_dwordx4 v[212:213], off
	s_setprio 1
	s_waitcnt vmcnt(8) lgkmcnt(0)
	s_barrier
	v_mfma_f32_16x16x32_bf16 v[62:65], v[66:69], v[186:189], v[62:65]
	v_mfma_f32_16x16x32_bf16 v[58:61], v[74:77], v[186:189], v[58:61]
	v_mfma_f32_16x16x32_bf16 v[46:49], v[66:69], v[194:197], v[46:49]
	v_mfma_f32_16x16x32_bf16 v[42:45], v[74:77], v[194:197], v[42:45]
	v_mfma_f32_16x16x32_bf16 v[30:33], v[66:69], v[202:205], v[30:33]
	v_mfma_f32_16x16x32_bf16 v[26:29], v[74:77], v[202:205], v[26:29]
	v_mfma_f32_16x16x32_bf16 v[14:17], v[66:69], v[216:219], v[14:17]
	v_mfma_f32_16x16x32_bf16 v[10:13], v[74:77], v[216:219], v[10:13]
	v_mfma_f32_16x16x32_bf16 v[62:65], v[70:73], v[190:193], v[62:65]
	v_mfma_f32_16x16x32_bf16 v[58:61], v[78:81], v[190:193], v[58:61]
	v_mfma_f32_16x16x32_bf16 v[46:49], v[70:73], v[198:201], v[46:49]
	v_mfma_f32_16x16x32_bf16 v[42:45], v[78:81], v[198:201], v[42:45]
	v_mfma_f32_16x16x32_bf16 v[30:33], v[70:73], v[206:209], v[30:33]
	v_mfma_f32_16x16x32_bf16 v[26:29], v[78:81], v[206:209], v[26:29]
	v_mfma_f32_16x16x32_bf16 v[14:17], v[70:73], v[220:223], v[14:17]
	v_mfma_f32_16x16x32_bf16 v[10:13], v[78:81], v[220:223], v[10:13]
	v_mfma_f32_16x16x32_bf16 v[54:57], v[82:85], v[186:189], v[54:57]
	v_mfma_f32_16x16x32_bf16 v[50:53], v[90:93], v[186:189], v[50:53]
	v_mfma_f32_16x16x32_bf16 v[38:41], v[82:85], v[194:197], v[38:41]
	v_mfma_f32_16x16x32_bf16 v[34:37], v[90:93], v[194:197], v[34:37]
	v_mfma_f32_16x16x32_bf16 v[22:25], v[82:85], v[202:205], v[22:25]
	v_mfma_f32_16x16x32_bf16 v[18:21], v[90:93], v[202:205], v[18:21]
	v_mfma_f32_16x16x32_bf16 v[6:9], v[82:85], v[216:219], v[6:9]
	v_mfma_f32_16x16x32_bf16 v[2:5], v[90:93], v[216:219], v[2:5]
	v_mfma_f32_16x16x32_bf16 v[54:57], v[86:89], v[190:193], v[54:57]
	v_mfma_f32_16x16x32_bf16 v[50:53], v[98:101], v[190:193], v[50:53]
	v_mfma_f32_16x16x32_bf16 v[38:41], v[86:89], v[198:201], v[38:41]
	v_mfma_f32_16x16x32_bf16 v[34:37], v[98:101], v[198:201], v[34:37]
	v_mfma_f32_16x16x32_bf16 v[22:25], v[86:89], v[206:209], v[22:25]
	v_mfma_f32_16x16x32_bf16 v[18:21], v[98:101], v[206:209], v[18:21]
	v_mfma_f32_16x16x32_bf16 v[6:9], v[86:89], v[220:223], v[6:9]
	v_mfma_f32_16x16x32_bf16 v[2:5], v[98:101], v[220:223], v[2:5]
	s_setprio 0
	s_barrier
	s_add_i32 s51, s51, 2
	s_add_u32 s6, s6, 0x100
	s_addc_u32 s7, s7, 0
	s_add_u32 s49, s49, 0x100
	s_addc_u32 s50, s50, 0
	s_cmp_gt_u32 s51, 29
	s_cbranch_scc0 .LBB0_116
	s_and_b64 vcc, exec, s[18:19]
	s_cbranch_vccz .LBB0_119
	s_barrier

.LBB0_226:
	s_add_u32 s30, s8, 0xfff80080
	s_addc_u32 s31, s9, -1
	s_add_i32 s54, 0, 0x10000
	s_cmp_eq_u32 s53, 28
	s_cselect_b32 s35, s23, s31
	s_cselect_b32 s34, s28, s30
	s_cselect_b32 s31, s21, s52
	s_cselect_b32 s30, s29, s51
	s_add_i32 s56, 0, 0x14000
	v_add_u32_e32 v160, s54, v141
	v_add_u32_e32 v176, s56, v141
	ds_read_b128 v[148:151], v160
	ds_read_b128 v[152:155], v160 offset:1024
	ds_read_b128 v[156:159], v160 offset:2048
	ds_read_b128 v[160:163], v160 offset:3072
	ds_read_b128 v[164:167], v176
	ds_read_b128 v[168:171], v176 offset:1024
	ds_read_b128 v[172:175], v176 offset:2048
	ds_read_b128 v[176:179], v176 offset:3072
	v_lshl_add_u64 v[208:209], s[8:9], 0, v[144:145]
	s_add_i32 m0, s41, 0xc000
	ds_read_b128 v[180:183], v238
	ds_read_b128 v[184:187], v238 offset:1024
	ds_read_b128 v[188:191], v238 offset:2048
	ds_read_b128 v[192:195], v238 offset:3072
	ds_read_b128 v[196:199], v238 offset:4096
	ds_read_b128 v[200:203], v238 offset:5120
	ds_read_b128 v[204:207], v238 offset:6144
	ds_read_b128 v[216:219], v238 offset:7168
	global_load_lds_dwordx4 v[208:209], off
	v_lshl_add_u64 v[208:209], s[8:9], 0, v[146:147]
	s_add_i32 m0, s41, 0xe000
	s_nop 0
	global_load_lds_dwordx4 v[208:209], off
	s_setprio 1
	s_waitcnt vmcnt(8) lgkmcnt(0)
	s_barrier
	v_mfma_f32_16x16x32_bf16 v[126:129], v[148:151], v[180:183], v[126:129]
	v_mfma_f32_16x16x32_bf16 v[122:125], v[156:159], v[180:183], v[122:125]
	v_mfma_f32_16x16x32_bf16 v[110:113], v[148:151], v[188:191], v[110:113]
	v_mfma_f32_16x16x32_bf16 v[106:109], v[156:159], v[188:191], v[106:109]
	v_mfma_f32_16x16x32_bf16 v[94:97], v[148:151], v[196:199], v[94:97]
	v_mfma_f32_16x16x32_bf16 v[90:93], v[156:159], v[196:199], v[90:93]
	v_mfma_f32_16x16x32_bf16 v[78:81], v[148:151], v[204:207], v[78:81]
	v_mfma_f32_16x16x32_bf16 v[74:77], v[156:159], v[204:207], v[74:77]
	v_mfma_f32_16x16x32_bf16 v[126:129], v[152:155], v[184:187], v[126:129]
	v_mfma_f32_16x16x32_bf16 v[122:125], v[160:163], v[184:187], v[122:125]
	v_mfma_f32_16x16x32_bf16 v[110:113], v[152:155], v[192:195], v[110:113]
	v_mfma_f32_16x16x32_bf16 v[106:109], v[160:163], v[192:195], v[106:109]
	v_mfma_f32_16x16x32_bf16 v[94:97], v[152:155], v[200:203], v[94:97]
	v_mfma_f32_16x16x32_bf16 v[90:93], v[160:163], v[200:203], v[90:93]
	v_mfma_f32_16x16x32_bf16 v[78:81], v[152:155], v[216:219], v[78:81]
	v_mfma_f32_16x16x32_bf16 v[74:77], v[160:163], v[216:219], v[74:77]
	v_mfma_f32_16x16x32_bf16 v[118:121], v[164:167], v[180:183], v[118:121]
	v_mfma_f32_16x16x32_bf16 v[114:117], v[172:175], v[180:183], v[114:117]
	v_mfma_f32_16x16x32_bf16 v[102:105], v[164:167], v[188:191], v[102:105]
	v_mfma_f32_16x16x32_bf16 v[98:101], v[172:175], v[188:191], v[98:101]
	v_mfma_f32_16x16x32_bf16 v[86:89], v[164:167], v[196:199], v[86:89]
	v_mfma_f32_16x16x32_bf16 v[82:85], v[172:175], v[196:199], v[82:85]
	v_mfma_f32_16x16x32_bf16 v[70:73], v[164:167], v[204:207], v[70:73]
	v_mfma_f32_16x16x32_bf16 v[66:69], v[172:175], v[204:207], v[66:69]
	v_mfma_f32_16x16x32_bf16 v[118:121], v[168:171], v[184:187], v[118:121]
	v_mfma_f32_16x16x32_bf16 v[114:117], v[176:179], v[184:187], v[114:117]
	v_mfma_f32_16x16x32_bf16 v[102:105], v[168:171], v[192:195], v[102:105]
	v_mfma_f32_16x16x32_bf16 v[98:101], v[176:179], v[192:195], v[98:101]
	v_mfma_f32_16x16x32_bf16 v[86:89], v[168:171], v[200:203], v[86:89]
	v_mfma_f32_16x16x32_bf16 v[82:85], v[176:179], v[200:203], v[82:85]
	v_mfma_f32_16x16x32_bf16 v[70:73], v[168:171], v[216:219], v[70:73]
	v_mfma_f32_16x16x32_bf16 v[66:69], v[176:179], v[216:219], v[66:69]
	s_setprio 0
	s_barrier
	s_add_i32 s54, s54, s40
	v_lshl_add_u64 v[208:209], s[30:31], 0, v[134:135]
	s_mov_b32 m0, s54
	ds_read_b128 v[180:183], v238 offset:16384
	ds_read_b128 v[184:187], v238 offset:17408
	ds_read_b128 v[188:191], v238 offset:18432
	ds_read_b128 v[192:195], v238 offset:19456
	ds_read_b128 v[196:199], v238 offset:20480
	ds_read_b128 v[200:203], v238 offset:21504
	ds_read_b128 v[204:207], v238 offset:22528
	ds_read_b128 v[216:219], v238 offset:23552
	global_load_lds_dwordx4 v[208:209], off
	s_add_i32 m0, s54, 0x2000
	s_add_u32 s54, s30, 0x80000
	v_lshl_add_u64 v[212:213], s[30:31], 0, v[130:131]
	s_addc_u32 s55, s31, 0
	s_add_i32 s56, s56, s40
	global_load_lds_dwordx4 v[212:213], off
	v_lshl_add_u64 v[214:215], s[54:55], 0, v[134:135]
	s_mov_b32 m0, s56
	v_lshl_add_u64 v[220:221], s[34:35], 0, v[132:133]
	global_load_lds_dwordx4 v[214:215], off
	v_lshl_add_u64 v[214:215], s[54:55], 0, v[130:131]
	s_add_i32 m0, s56, 0x2000
	s_nop 0
	global_load_lds_dwordx4 v[214:215], off
	v_lshl_add_u64 v[214:215], s[34:35], 0, v[136:137]
	s_mov_b32 m0, s41
	s_nop 0
	global_load_lds_dwordx4 v[214:215], off
	s_mov_b32 m0, s42
	s_nop 0
	global_load_lds_dwordx4 v[220:221], off
	s_setprio 1
	s_waitcnt vmcnt(8) lgkmcnt(0)
	s_barrier
	v_mfma_f32_16x16x32_bf16 v[62:65], v[148:151], v[180:183], v[62:65]
	v_mfma_f32_16x16x32_bf16 v[58:61], v[156:159], v[180:183], v[58:61]
	v_mfma_f32_16x16x32_bf16 v[46:49], v[148:151], v[188:191], v[46:49]
	v_mfma_f32_16x16x32_bf16 v[42:45], v[156:159], v[188:191], v[42:45]
	v_mfma_f32_16x16x32_bf16 v[30:33], v[148:151], v[196:199], v[30:33]
	v_mfma_f32_16x16x32_bf16 v[26:29], v[156:159], v[196:199], v[26:29]
	v_mfma_f32_16x16x32_bf16 v[14:17], v[148:151], v[204:207], v[14:17]
	v_mfma_f32_16x16x32_bf16 v[10:13], v[156:159], v[204:207], v[10:13]
	v_mfma_f32_16x16x32_bf16 v[62:65], v[152:155], v[184:187], v[62:65]
	v_mfma_f32_16x16x32_bf16 v[58:61], v[160:163], v[184:187], v[58:61]
	v_mfma_f32_16x16x32_bf16 v[46:49], v[152:155], v[192:195], v[46:49]
	v_mfma_f32_16x16x32_bf16 v[42:45], v[160:163], v[192:195], v[42:45]
	v_mfma_f32_16x16x32_bf16 v[30:33], v[152:155], v[200:203], v[30:33]
	v_mfma_f32_16x16x32_bf16 v[26:29], v[160:163], v[200:203], v[26:29]
	v_mfma_f32_16x16x32_bf16 v[14:17], v[152:155], v[216:219], v[14:17]
	v_mfma_f32_16x16x32_bf16 v[10:13], v[160:163], v[216:219], v[10:13]
	v_mfma_f32_16x16x32_bf16 v[54:57], v[164:167], v[180:183], v[54:57]
	v_mfma_f32_16x16x32_bf16 v[50:53], v[172:175], v[180:183], v[50:53]
	v_mfma_f32_16x16x32_bf16 v[38:41], v[164:167], v[188:191], v[38:41]
	v_mfma_f32_16x16x32_bf16 v[34:37], v[172:175], v[188:191], v[34:37]
	v_mfma_f32_16x16x32_bf16 v[22:25], v[164:167], v[196:199], v[22:25]
	v_mfma_f32_16x16x32_bf16 v[18:21], v[172:175], v[196:199], v[18:21]
	v_mfma_f32_16x16x32_bf16 v[6:9], v[164:167], v[204:207], v[6:9]
	v_mfma_f32_16x16x32_bf16 v[2:5], v[172:175], v[204:207], v[2:5]
	v_mfma_f32_16x16x32_bf16 v[54:57], v[168:171], v[184:187], v[54:57]
	v_mfma_f32_16x16x32_bf16 v[50:53], v[176:179], v[184:187], v[50:53]
	v_mfma_f32_16x16x32_bf16 v[38:41], v[168:171], v[192:195], v[38:41]
	v_mfma_f32_16x16x32_bf16 v[34:37], v[176:179], v[192:195], v[34:37]
	v_mfma_f32_16x16x32_bf16 v[22:25], v[168:171], v[200:203], v[22:25]
	v_mfma_f32_16x16x32_bf16 v[18:21], v[176:179], v[200:203], v[18:21]
	v_mfma_f32_16x16x32_bf16 v[6:9], v[168:171], v[216:219], v[6:9]
	v_mfma_f32_16x16x32_bf16 v[2:5], v[176:179], v[216:219], v[2:5]
	s_setprio 0
	s_barrier
	s_add_i32 s54, 0, 0x18000
	s_add_i32 s55, 0, 0x1c000
	v_add_u32_e32 v160, s54, v141
	v_add_u32_e32 v176, s55, v141
	ds_read_b128 v[148:151], v160
	ds_read_b128 v[152:155], v160 offset:1024
	ds_read_b128 v[156:159], v160 offset:2048
	ds_read_b128 v[160:163], v160 offset:3072
	ds_read_b128 v[164:167], v176
	ds_read_b128 v[168:171], v176 offset:1024
	ds_read_b128 v[172:175], v176 offset:2048
	ds_read_b128 v[176:179], v176 offset:3072
	s_add_u32 s34, s34, 0x80000
	s_addc_u32 s35, s35, 0
	s_mov_b32 m0, s43
	v_lshl_add_u64 v[222:223], s[34:35], 0, v[136:137]
	ds_read_b128 v[180:183], v238 offset:32768
	ds_read_b128 v[184:187], v238 offset:33792
	ds_read_b128 v[188:191], v238 offset:34816
	ds_read_b128 v[192:195], v238 offset:35840
	ds_read_b128 v[196:199], v238 offset:36864
	ds_read_b128 v[200:203], v238 offset:37888
	ds_read_b128 v[204:207], v238 offset:38912
	ds_read_b128 v[216:219], v238 offset:39936
	global_load_lds_dwordx4 v[222:223], off
	v_lshl_add_u64 v[222:223], s[34:35], 0, v[132:133]
	s_mov_b32 m0, s44
	s_nop 0
	global_load_lds_dwordx4 v[222:223], off
	s_setprio 1
	s_waitcnt vmcnt(8) lgkmcnt(0)
	s_barrier
	v_mfma_f32_16x16x32_bf16 v[126:129], v[148:151], v[180:183], v[126:129]
	v_mfma_f32_16x16x32_bf16 v[122:125], v[156:159], v[180:183], v[122:125]
	v_mfma_f32_16x16x32_bf16 v[110:113], v[148:151], v[188:191], v[110:113]
	v_mfma_f32_16x16x32_bf16 v[106:109], v[156:159], v[188:191], v[106:109]
	v_mfma_f32_16x16x32_bf16 v[94:97], v[148:151], v[196:199], v[94:97]
	v_mfma_f32_16x16x32_bf16 v[90:93], v[156:159], v[196:199], v[90:93]
	v_mfma_f32_16x16x32_bf16 v[78:81], v[148:151], v[204:207], v[78:81]
	v_mfma_f32_16x16x32_bf16 v[74:77], v[156:159], v[204:207], v[74:77]
	v_mfma_f32_16x16x32_bf16 v[126:129], v[152:155], v[184:187], v[126:129]
	v_mfma_f32_16x16x32_bf16 v[122:125], v[160:163], v[184:187], v[122:125]
	v_mfma_f32_16x16x32_bf16 v[110:113], v[152:155], v[192:195], v[110:113]
	v_mfma_f32_16x16x32_bf16 v[106:109], v[160:163], v[192:195], v[106:109]
	v_mfma_f32_16x16x32_bf16 v[94:97], v[152:155], v[200:203], v[94:97]
	v_mfma_f32_16x16x32_bf16 v[90:93], v[160:163], v[200:203], v[90:93]
	v_mfma_f32_16x16x32_bf16 v[78:81], v[152:155], v[216:219], v[78:81]
	v_mfma_f32_16x16x32_bf16 v[74:77], v[160:163], v[216:219], v[74:77]
	v_mfma_f32_16x16x32_bf16 v[118:121], v[164:167], v[180:183], v[118:121]
	v_mfma_f32_16x16x32_bf16 v[114:117], v[172:175], v[180:183], v[114:117]
	v_mfma_f32_16x16x32_bf16 v[102:105], v[164:167], v[188:191], v[102:105]
	v_mfma_f32_16x16x32_bf16 v[98:101], v[172:175], v[188:191], v[98:101]
	v_mfma_f32_16x16x32_bf16 v[86:89], v[164:167], v[196:199], v[86:89]
	v_mfma_f32_16x16x32_bf16 v[82:85], v[172:175], v[196:199], v[82:85]
	v_mfma_f32_16x16x32_bf16 v[70:73], v[164:167], v[204:207], v[70:73]
	v_mfma_f32_16x16x32_bf16 v[66:69], v[172:175], v[204:207], v[66:69]
	v_mfma_f32_16x16x32_bf16 v[118:121], v[168:171], v[184:187], v[118:121]
	v_mfma_f32_16x16x32_bf16 v[114:117], v[176:179], v[184:187], v[114:117]
	v_mfma_f32_16x16x32_bf16 v[102:105], v[168:171], v[192:195], v[102:105]
	v_mfma_f32_16x16x32_bf16 v[98:101], v[176:179], v[192:195], v[98:101]
	v_mfma_f32_16x16x32_bf16 v[86:89], v[168:171], v[200:203], v[86:89]
	v_mfma_f32_16x16x32_bf16 v[82:85], v[176:179], v[200:203], v[82:85]
	v_mfma_f32_16x16x32_bf16 v[70:73], v[168:171], v[216:219], v[70:73]
	v_mfma_f32_16x16x32_bf16 v[66:69], v[176:179], v[216:219], v[66:69]
	s_setprio 0
	s_barrier
	s_add_i32 s34, s54, s40
	v_lshl_add_u64 v[208:209], v[208:209], 0, s[64:65]
	s_mov_b32 m0, s34
	ds_read_b128 v[180:183], v238 offset:49152
	ds_read_b128 v[184:187], v238 offset:50176
	ds_read_b128 v[188:191], v238 offset:51200
	ds_read_b128 v[192:195], v238 offset:52224
	ds_read_b128 v[196:199], v238 offset:53248
	ds_read_b128 v[200:203], v238 offset:54272
	ds_read_b128 v[204:207], v238 offset:55296
	ds_read_b128 v[216:219], v238 offset:56320
	global_load_lds_dwordx4 v[208:209], off
	s_add_i32 m0, s34, 0x2000
	s_add_u32 s30, s30, 0x80080
	v_lshl_add_u64 v[208:209], v[212:213], 0, s[64:65]
	s_addc_u32 s31, s31, 0
	s_add_i32 s34, s55, s40
	global_load_lds_dwordx4 v[208:209], off
	v_lshl_add_u64 v[208:209], s[30:31], 0, v[134:135]
	s_mov_b32 m0, s34
	s_nop 0
	global_load_lds_dwordx4 v[208:209], off
	v_lshl_add_u64 v[208:209], s[30:31], 0, v[130:131]
	s_add_i32 m0, s34, 0x2000
	s_nop 0
	global_load_lds_dwordx4 v[208:209], off
	v_lshl_add_u64 v[208:209], v[214:215], 0, s[64:65]
	s_mov_b32 m0, s46
	s_nop 0
	global_load_lds_dwordx4 v[208:209], off
	v_lshl_add_u64 v[208:209], v[220:221], 0, s[64:65]
	s_mov_b32 m0, s47
	s_nop 0
	global_load_lds_dwordx4 v[208:209], off
	s_setprio 1
	s_waitcnt vmcnt(8) lgkmcnt(0)
	s_barrier
	v_mfma_f32_16x16x32_bf16 v[62:65], v[148:151], v[180:183], v[62:65]
	v_mfma_f32_16x16x32_bf16 v[58:61], v[156:159], v[180:183], v[58:61]
	v_mfma_f32_16x16x32_bf16 v[46:49], v[148:151], v[188:191], v[46:49]
	v_mfma_f32_16x16x32_bf16 v[42:45], v[156:159], v[188:191], v[42:45]
	v_mfma_f32_16x16x32_bf16 v[30:33], v[148:151], v[196:199], v[30:33]
	v_mfma_f32_16x16x32_bf16 v[26:29], v[156:159], v[196:199], v[26:29]
	v_mfma_f32_16x16x32_bf16 v[14:17], v[148:151], v[204:207], v[14:17]
	v_mfma_f32_16x16x32_bf16 v[10:13], v[156:159], v[204:207], v[10:13]
	v_mfma_f32_16x16x32_bf16 v[62:65], v[152:155], v[184:187], v[62:65]
	v_mfma_f32_16x16x32_bf16 v[58:61], v[160:163], v[184:187], v[58:61]
	v_mfma_f32_16x16x32_bf16 v[46:49], v[152:155], v[192:195], v[46:49]
	v_mfma_f32_16x16x32_bf16 v[42:45], v[160:163], v[192:195], v[42:45]
	v_mfma_f32_16x16x32_bf16 v[30:33], v[152:155], v[200:203], v[30:33]
	v_mfma_f32_16x16x32_bf16 v[26:29], v[160:163], v[200:203], v[26:29]
	v_mfma_f32_16x16x32_bf16 v[14:17], v[152:155], v[216:219], v[14:17]
	v_mfma_f32_16x16x32_bf16 v[10:13], v[160:163], v[216:219], v[10:13]
	v_mfma_f32_16x16x32_bf16 v[54:57], v[164:167], v[180:183], v[54:57]
	v_mfma_f32_16x16x32_bf16 v[50:53], v[172:175], v[180:183], v[50:53]
	v_mfma_f32_16x16x32_bf16 v[38:41], v[164:167], v[188:191], v[38:41]
	v_mfma_f32_16x16x32_bf16 v[34:37], v[172:175], v[188:191], v[34:37]
	v_mfma_f32_16x16x32_bf16 v[22:25], v[164:167], v[196:199], v[22:25]
	v_mfma_f32_16x16x32_bf16 v[18:21], v[172:175], v[196:199], v[18:21]
	v_mfma_f32_16x16x32_bf16 v[6:9], v[164:167], v[204:207], v[6:9]
	v_mfma_f32_16x16x32_bf16 v[2:5], v[172:175], v[204:207], v[2:5]
	v_mfma_f32_16x16x32_bf16 v[54:57], v[168:171], v[184:187], v[54:57]
	v_mfma_f32_16x16x32_bf16 v[50:53], v[176:179], v[184:187], v[50:53]
	v_mfma_f32_16x16x32_bf16 v[38:41], v[168:171], v[192:195], v[38:41]
	v_mfma_f32_16x16x32_bf16 v[34:37], v[176:179], v[192:195], v[34:37]
	v_mfma_f32_16x16x32_bf16 v[22:25], v[168:171], v[200:203], v[22:25]
	v_mfma_f32_16x16x32_bf16 v[18:21], v[176:179], v[200:203], v[18:21]
	v_mfma_f32_16x16x32_bf16 v[6:9], v[168:171], v[216:219], v[6:9]
	v_mfma_f32_16x16x32_bf16 v[2:5], v[176:179], v[216:219], v[2:5]
	s_setprio 0
	s_barrier
	s_add_i32 s53, s53, 2
	s_add_u32 s8, s8, 0x100
	s_addc_u32 s9, s9, 0
	s_add_u32 s51, s51, 0x100
	s_addc_u32 s52, s52, 0
	s_cmp_gt_u32 s53, 29
	s_cbranch_scc0 .LBB0_226
	s_and_b64 vcc, exec, s[18:19]
	s_cbranch_vccz .LBB0_229
	s_barrier

.LBB0_956:
	s_add_u32 s10, s34, 0x100
	s_addc_u32 s11, s35, 0
	s_add_i32 s63, 0, 0x10000
	s_cmp_eq_u32 s62, 28
	s_cselect_b32 s47, s2, s11
	s_cselect_b32 s46, s3, s10
	s_cselect_b32 s43, s31, s61
	s_cselect_b32 s42, s37, s60
	s_add_i32 s66, 0, 0x14000
	v_add_u32_e32 v78, s63, v251
	v_add_u32_e32 v94, s66, v251
	ds_read_b128 v[66:69], v78
	ds_read_b128 v[70:73], v78 offset:1024
	ds_read_b128 v[74:77], v78 offset:2048
	ds_read_b128 v[78:81], v78 offset:3072
	ds_read_b128 v[82:85], v94
	ds_read_b128 v[86:89], v94 offset:1024
	ds_read_b128 v[90:93], v94 offset:2048
	ds_read_b128 v[94:97], v94 offset:3072
	v_lshl_add_u64 v[194:195], s[34:35], 0, v[218:219]
	s_add_i32 m0, s51, 0xc000
	ds_read_b128 v[162:165], v244
	ds_read_b128 v[166:169], v244 offset:1024
	ds_read_b128 v[170:173], v244 offset:2048
	ds_read_b128 v[174:177], v244 offset:3072
	ds_read_b128 v[178:181], v244 offset:4096
	ds_read_b128 v[182:185], v244 offset:5120
	ds_read_b128 v[186:189], v244 offset:6144
	ds_read_b128 v[190:193], v244 offset:7168
	global_load_lds_dwordx4 v[194:195], off
	v_lshl_add_u64 v[194:195], s[34:35], 0, v[220:221]
	s_add_i32 m0, s51, 0xe000
	s_nop 0
	global_load_lds_dwordx4 v[194:195], off
	s_setprio 1
	s_waitcnt vmcnt(8) lgkmcnt(0)
	s_barrier
	v_mfma_f32_16x16x32_bf16 v[158:161], v[66:69], v[162:165], v[158:161]
	v_mfma_f32_16x16x32_bf16 v[154:157], v[74:77], v[162:165], v[154:157]
	v_mfma_f32_16x16x32_bf16 v[142:145], v[66:69], v[170:173], v[142:145]
	v_mfma_f32_16x16x32_bf16 v[138:141], v[74:77], v[170:173], v[138:141]
	v_mfma_f32_16x16x32_bf16 v[126:129], v[66:69], v[178:181], v[126:129]
	v_mfma_f32_16x16x32_bf16 v[122:125], v[74:77], v[178:181], v[122:125]
	v_mfma_f32_16x16x32_bf16 v[110:113], v[66:69], v[186:189], v[110:113]
	v_mfma_f32_16x16x32_bf16 v[106:109], v[74:77], v[186:189], v[106:109]
	v_mfma_f32_16x16x32_bf16 v[158:161], v[70:73], v[166:169], v[158:161]
	v_mfma_f32_16x16x32_bf16 v[154:157], v[78:81], v[166:169], v[154:157]
	v_mfma_f32_16x16x32_bf16 v[142:145], v[70:73], v[174:177], v[142:145]
	v_mfma_f32_16x16x32_bf16 v[138:141], v[78:81], v[174:177], v[138:141]
	v_mfma_f32_16x16x32_bf16 v[126:129], v[70:73], v[182:185], v[126:129]
	v_mfma_f32_16x16x32_bf16 v[122:125], v[78:81], v[182:185], v[122:125]
	v_mfma_f32_16x16x32_bf16 v[110:113], v[70:73], v[190:193], v[110:113]
	v_mfma_f32_16x16x32_bf16 v[106:109], v[78:81], v[190:193], v[106:109]
	v_mfma_f32_16x16x32_bf16 v[150:153], v[82:85], v[162:165], v[150:153]
	v_mfma_f32_16x16x32_bf16 v[146:149], v[90:93], v[162:165], v[146:149]
	v_mfma_f32_16x16x32_bf16 v[134:137], v[82:85], v[170:173], v[134:137]
	v_mfma_f32_16x16x32_bf16 v[130:133], v[90:93], v[170:173], v[130:133]
	v_mfma_f32_16x16x32_bf16 v[118:121], v[82:85], v[178:181], v[118:121]
	v_mfma_f32_16x16x32_bf16 v[114:117], v[90:93], v[178:181], v[114:117]
	v_mfma_f32_16x16x32_bf16 v[102:105], v[82:85], v[186:189], v[102:105]
	v_mfma_f32_16x16x32_bf16 v[98:101], v[90:93], v[186:189], v[98:101]
	v_mfma_f32_16x16x32_bf16 v[150:153], v[86:89], v[166:169], v[150:153]
	v_mfma_f32_16x16x32_bf16 v[146:149], v[94:97], v[166:169], v[146:149]
	v_mfma_f32_16x16x32_bf16 v[134:137], v[86:89], v[174:177], v[134:137]
	v_mfma_f32_16x16x32_bf16 v[130:133], v[94:97], v[174:177], v[130:133]
	v_mfma_f32_16x16x32_bf16 v[118:121], v[86:89], v[182:185], v[118:121]
	v_mfma_f32_16x16x32_bf16 v[114:117], v[94:97], v[182:185], v[114:117]
	v_mfma_f32_16x16x32_bf16 v[102:105], v[86:89], v[190:193], v[102:105]
	v_mfma_f32_16x16x32_bf16 v[98:101], v[94:97], v[190:193], v[98:101]
	s_setprio 0
	s_barrier
	s_add_i32 s34, s63, s44
	v_lshl_add_u64 v[194:195], s[42:43], 0, v[210:211]
	s_mov_b32 m0, s34
	ds_read_b128 v[162:165], v244 offset:16384
	ds_read_b128 v[166:169], v244 offset:17408
	ds_read_b128 v[170:173], v244 offset:18432
	ds_read_b128 v[174:177], v244 offset:19456
	ds_read_b128 v[178:181], v244 offset:20480
	ds_read_b128 v[182:185], v244 offset:21504
	ds_read_b128 v[186:189], v244 offset:22528
	ds_read_b128 v[190:193], v244 offset:23552
	global_load_lds_dwordx4 v[194:195], off
	s_add_i32 m0, s34, 0x2000
	s_add_u32 s34, s42, 0x80000
	v_lshl_add_u64 v[196:197], s[42:43], 0, v[216:217]
	s_addc_u32 s35, s43, 0
	s_add_i32 s63, s66, s44
	global_load_lds_dwordx4 v[196:197], off
	v_lshl_add_u64 v[198:199], s[34:35], 0, v[210:211]
	s_mov_b32 m0, s63
	v_lshl_add_u64 v[200:201], s[46:47], 0, v[216:217]
	global_load_lds_dwordx4 v[198:199], off
	v_lshl_add_u64 v[198:199], s[34:35], 0, v[216:217]
	s_add_i32 m0, s63, 0x2000
	s_nop 0
	global_load_lds_dwordx4 v[198:199], off
	v_lshl_add_u64 v[198:199], s[46:47], 0, v[210:211]
	s_mov_b32 m0, s51
	s_nop 0
	global_load_lds_dwordx4 v[198:199], off
	s_mov_b32 m0, s52
	s_nop 0
	global_load_lds_dwordx4 v[200:201], off
	s_setprio 1
	s_waitcnt vmcnt(8) lgkmcnt(0)
	s_barrier
	v_mfma_f32_16x16x32_bf16 v[62:65], v[66:69], v[162:165], v[62:65]
	v_mfma_f32_16x16x32_bf16 v[58:61], v[74:77], v[162:165], v[58:61]
	v_mfma_f32_16x16x32_bf16 v[46:49], v[66:69], v[170:173], v[46:49]
	v_mfma_f32_16x16x32_bf16 v[42:45], v[74:77], v[170:173], v[42:45]
	v_mfma_f32_16x16x32_bf16 v[30:33], v[66:69], v[178:181], v[30:33]
	v_mfma_f32_16x16x32_bf16 v[26:29], v[74:77], v[178:181], v[26:29]
	v_mfma_f32_16x16x32_bf16 v[14:17], v[66:69], v[186:189], v[14:17]
	v_mfma_f32_16x16x32_bf16 v[10:13], v[74:77], v[186:189], v[10:13]
	v_mfma_f32_16x16x32_bf16 v[62:65], v[70:73], v[166:169], v[62:65]
	v_mfma_f32_16x16x32_bf16 v[58:61], v[78:81], v[166:169], v[58:61]
	v_mfma_f32_16x16x32_bf16 v[46:49], v[70:73], v[174:177], v[46:49]
	v_mfma_f32_16x16x32_bf16 v[42:45], v[78:81], v[174:177], v[42:45]
	v_mfma_f32_16x16x32_bf16 v[30:33], v[70:73], v[182:185], v[30:33]
	v_mfma_f32_16x16x32_bf16 v[26:29], v[78:81], v[182:185], v[26:29]
	v_mfma_f32_16x16x32_bf16 v[14:17], v[70:73], v[190:193], v[14:17]
	v_mfma_f32_16x16x32_bf16 v[10:13], v[78:81], v[190:193], v[10:13]
	v_mfma_f32_16x16x32_bf16 v[54:57], v[82:85], v[162:165], v[54:57]
	v_mfma_f32_16x16x32_bf16 v[50:53], v[90:93], v[162:165], v[50:53]
	v_mfma_f32_16x16x32_bf16 v[38:41], v[82:85], v[170:173], v[38:41]
	v_mfma_f32_16x16x32_bf16 v[34:37], v[90:93], v[170:173], v[34:37]
	v_mfma_f32_16x16x32_bf16 v[22:25], v[82:85], v[178:181], v[22:25]
	v_mfma_f32_16x16x32_bf16 v[18:21], v[90:93], v[178:181], v[18:21]
	v_mfma_f32_16x16x32_bf16 v[6:9], v[82:85], v[186:189], v[6:9]
	v_mfma_f32_16x16x32_bf16 v[2:5], v[90:93], v[186:189], v[2:5]
	v_mfma_f32_16x16x32_bf16 v[54:57], v[86:89], v[166:169], v[54:57]
	v_mfma_f32_16x16x32_bf16 v[50:53], v[94:97], v[166:169], v[50:53]
	v_mfma_f32_16x16x32_bf16 v[38:41], v[86:89], v[174:177], v[38:41]
	v_mfma_f32_16x16x32_bf16 v[34:37], v[94:97], v[174:177], v[34:37]
	v_mfma_f32_16x16x32_bf16 v[22:25], v[86:89], v[182:185], v[22:25]
	v_mfma_f32_16x16x32_bf16 v[18:21], v[94:97], v[182:185], v[18:21]
	v_mfma_f32_16x16x32_bf16 v[6:9], v[86:89], v[190:193], v[6:9]
	v_mfma_f32_16x16x32_bf16 v[2:5], v[94:97], v[190:193], v[2:5]
	s_setprio 0
	s_barrier
	s_add_i32 s63, 0, 0x18000
	s_add_i32 s66, 0, 0x1c000
	v_add_u32_e32 v78, s63, v251
	v_add_u32_e32 v94, s66, v251
	ds_read_b128 v[66:69], v78
	ds_read_b128 v[70:73], v78 offset:1024
	ds_read_b128 v[74:77], v78 offset:2048
	ds_read_b128 v[78:81], v78 offset:3072
	ds_read_b128 v[82:85], v94
	ds_read_b128 v[86:89], v94 offset:1024
	ds_read_b128 v[90:93], v94 offset:2048
	ds_read_b128 v[94:97], v94 offset:3072
	s_add_u32 s34, s46, 0x80000
	s_addc_u32 s35, s47, 0
	s_mov_b32 m0, s53
	v_lshl_add_u64 v[202:203], s[34:35], 0, v[210:211]
	ds_read_b128 v[162:165], v244 offset:32768
	ds_read_b128 v[166:169], v244 offset:33792
	ds_read_b128 v[170:173], v244 offset:34816
	ds_read_b128 v[174:177], v244 offset:35840
	ds_read_b128 v[178:181], v244 offset:36864
	ds_read_b128 v[182:185], v244 offset:37888
	ds_read_b128 v[186:189], v244 offset:38912
	ds_read_b128 v[190:193], v244 offset:39936
	global_load_lds_dwordx4 v[202:203], off
	v_lshl_add_u64 v[202:203], s[34:35], 0, v[216:217]
	s_mov_b32 m0, s54
	s_nop 0
	global_load_lds_dwordx4 v[202:203], off
	s_setprio 1
	s_waitcnt vmcnt(8) lgkmcnt(0)
	s_barrier
	v_mfma_f32_16x16x32_bf16 v[158:161], v[66:69], v[162:165], v[158:161]
	v_mfma_f32_16x16x32_bf16 v[154:157], v[74:77], v[162:165], v[154:157]
	v_mfma_f32_16x16x32_bf16 v[142:145], v[66:69], v[170:173], v[142:145]
	v_mfma_f32_16x16x32_bf16 v[138:141], v[74:77], v[170:173], v[138:141]
	v_mfma_f32_16x16x32_bf16 v[126:129], v[66:69], v[178:181], v[126:129]
	v_mfma_f32_16x16x32_bf16 v[122:125], v[74:77], v[178:181], v[122:125]
	v_mfma_f32_16x16x32_bf16 v[110:113], v[66:69], v[186:189], v[110:113]
	v_mfma_f32_16x16x32_bf16 v[106:109], v[74:77], v[186:189], v[106:109]
	v_mfma_f32_16x16x32_bf16 v[158:161], v[70:73], v[166:169], v[158:161]
	v_mfma_f32_16x16x32_bf16 v[154:157], v[78:81], v[166:169], v[154:157]
	v_mfma_f32_16x16x32_bf16 v[142:145], v[70:73], v[174:177], v[142:145]
	v_mfma_f32_16x16x32_bf16 v[138:141], v[78:81], v[174:177], v[138:141]
	v_mfma_f32_16x16x32_bf16 v[126:129], v[70:73], v[182:185], v[126:129]
	v_mfma_f32_16x16x32_bf16 v[122:125], v[78:81], v[182:185], v[122:125]
	v_mfma_f32_16x16x32_bf16 v[110:113], v[70:73], v[190:193], v[110:113]
	v_mfma_f32_16x16x32_bf16 v[106:109], v[78:81], v[190:193], v[106:109]
	v_mfma_f32_16x16x32_bf16 v[150:153], v[82:85], v[162:165], v[150:153]
	v_mfma_f32_16x16x32_bf16 v[146:149], v[90:93], v[162:165], v[146:149]
	v_mfma_f32_16x16x32_bf16 v[134:137], v[82:85], v[170:173], v[134:137]
	v_mfma_f32_16x16x32_bf16 v[130:133], v[90:93], v[170:173], v[130:133]
	v_mfma_f32_16x16x32_bf16 v[118:121], v[82:85], v[178:181], v[118:121]
	v_mfma_f32_16x16x32_bf16 v[114:117], v[90:93], v[178:181], v[114:117]
	v_mfma_f32_16x16x32_bf16 v[102:105], v[82:85], v[186:189], v[102:105]
	v_mfma_f32_16x16x32_bf16 v[98:101], v[90:93], v[186:189], v[98:101]
	v_mfma_f32_16x16x32_bf16 v[150:153], v[86:89], v[166:169], v[150:153]
	v_mfma_f32_16x16x32_bf16 v[146:149], v[94:97], v[166:169], v[146:149]
	v_mfma_f32_16x16x32_bf16 v[134:137], v[86:89], v[174:177], v[134:137]
	v_mfma_f32_16x16x32_bf16 v[130:133], v[94:97], v[174:177], v[130:133]
	v_mfma_f32_16x16x32_bf16 v[118:121], v[86:89], v[182:185], v[118:121]
	v_mfma_f32_16x16x32_bf16 v[114:117], v[94:97], v[182:185], v[114:117]
	v_mfma_f32_16x16x32_bf16 v[102:105], v[86:89], v[190:193], v[102:105]
	v_mfma_f32_16x16x32_bf16 v[98:101], v[94:97], v[190:193], v[98:101]
	s_setprio 0
	s_barrier
	s_add_i32 s34, s63, s44
	v_lshl_add_u64 v[194:195], v[194:195], 0, s[64:65]
	s_mov_b32 m0, s34
	ds_read_b128 v[162:165], v244 offset:49152
	ds_read_b128 v[166:169], v244 offset:50176
	ds_read_b128 v[170:173], v244 offset:51200
	ds_read_b128 v[174:177], v244 offset:52224
	ds_read_b128 v[178:181], v244 offset:53248
	ds_read_b128 v[182:185], v244 offset:54272
	ds_read_b128 v[186:189], v244 offset:55296
	ds_read_b128 v[190:193], v244 offset:56320
	global_load_lds_dwordx4 v[194:195], off
	s_add_i32 m0, s34, 0x2000
	s_add_u32 s34, s42, 0x80080
	v_lshl_add_u64 v[194:195], v[196:197], 0, s[64:65]
	s_addc_u32 s35, s43, 0
	s_add_i32 s42, s66, s44
	global_load_lds_dwordx4 v[194:195], off
	v_lshl_add_u64 v[194:195], s[34:35], 0, v[210:211]
	s_mov_b32 m0, s42
	s_nop 0
	global_load_lds_dwordx4 v[194:195], off
	v_lshl_add_u64 v[194:195], s[34:35], 0, v[216:217]
	s_add_i32 m0, s42, 0x2000
	s_nop 0
	global_load_lds_dwordx4 v[194:195], off
	v_lshl_add_u64 v[194:195], v[198:199], 0, s[64:65]
	s_mov_b32 m0, s55
	s_nop 0
	global_load_lds_dwordx4 v[194:195], off
	v_lshl_add_u64 v[194:195], v[200:201], 0, s[64:65]
	s_mov_b32 m0, s56
	s_nop 0
	global_load_lds_dwordx4 v[194:195], off
	s_setprio 1
	s_waitcnt vmcnt(8) lgkmcnt(0)
	s_barrier
	v_mfma_f32_16x16x32_bf16 v[62:65], v[66:69], v[162:165], v[62:65]
	v_mfma_f32_16x16x32_bf16 v[58:61], v[74:77], v[162:165], v[58:61]
	v_mfma_f32_16x16x32_bf16 v[46:49], v[66:69], v[170:173], v[46:49]
	v_mfma_f32_16x16x32_bf16 v[42:45], v[74:77], v[170:173], v[42:45]
	v_mfma_f32_16x16x32_bf16 v[30:33], v[66:69], v[178:181], v[30:33]
	v_mfma_f32_16x16x32_bf16 v[26:29], v[74:77], v[178:181], v[26:29]
	v_mfma_f32_16x16x32_bf16 v[14:17], v[66:69], v[186:189], v[14:17]
	v_mfma_f32_16x16x32_bf16 v[10:13], v[74:77], v[186:189], v[10:13]
	v_mfma_f32_16x16x32_bf16 v[62:65], v[70:73], v[166:169], v[62:65]
	v_mfma_f32_16x16x32_bf16 v[58:61], v[78:81], v[166:169], v[58:61]
	v_mfma_f32_16x16x32_bf16 v[46:49], v[70:73], v[174:177], v[46:49]
	v_mfma_f32_16x16x32_bf16 v[42:45], v[78:81], v[174:177], v[42:45]
	v_mfma_f32_16x16x32_bf16 v[30:33], v[70:73], v[182:185], v[30:33]
	v_mfma_f32_16x16x32_bf16 v[26:29], v[78:81], v[182:185], v[26:29]
	v_mfma_f32_16x16x32_bf16 v[14:17], v[70:73], v[190:193], v[14:17]
	v_mfma_f32_16x16x32_bf16 v[10:13], v[78:81], v[190:193], v[10:13]
	v_mfma_f32_16x16x32_bf16 v[54:57], v[82:85], v[162:165], v[54:57]
	v_mfma_f32_16x16x32_bf16 v[50:53], v[90:93], v[162:165], v[50:53]
	v_mfma_f32_16x16x32_bf16 v[38:41], v[82:85], v[170:173], v[38:41]
	v_mfma_f32_16x16x32_bf16 v[34:37], v[90:93], v[170:173], v[34:37]
	v_mfma_f32_16x16x32_bf16 v[22:25], v[82:85], v[178:181], v[22:25]
	v_mfma_f32_16x16x32_bf16 v[18:21], v[90:93], v[178:181], v[18:21]
	v_mfma_f32_16x16x32_bf16 v[6:9], v[82:85], v[186:189], v[6:9]
	v_mfma_f32_16x16x32_bf16 v[2:5], v[90:93], v[186:189], v[2:5]
	v_mfma_f32_16x16x32_bf16 v[54:57], v[86:89], v[166:169], v[54:57]
	v_mfma_f32_16x16x32_bf16 v[50:53], v[94:97], v[166:169], v[50:53]
	v_mfma_f32_16x16x32_bf16 v[38:41], v[86:89], v[174:177], v[38:41]
	v_mfma_f32_16x16x32_bf16 v[34:37], v[94:97], v[174:177], v[34:37]
	v_mfma_f32_16x16x32_bf16 v[22:25], v[86:89], v[182:185], v[22:25]
	v_mfma_f32_16x16x32_bf16 v[18:21], v[94:97], v[182:185], v[18:21]
	v_mfma_f32_16x16x32_bf16 v[6:9], v[86:89], v[190:193], v[6:9]
	v_mfma_f32_16x16x32_bf16 v[2:5], v[94:97], v[190:193], v[2:5]
	s_setprio 0
	s_barrier
	s_add_i32 s62, s62, 2
	s_add_u32 s60, s60, 0x100
	s_addc_u32 s61, s61, 0
	s_cmp_gt_u32 s62, 29
	s_mov_b64 s[34:35], s[10:11]
	s_cbranch_scc0 .LBB0_956
	s_and_b64 vcc, exec, s[26:27]
	s_cbranch_vccz .LBB0_959
	s_barrier

.LBB0_1091:
	s_add_u32 s30, s26, 0xfff80080
	s_addc_u32 s31, s27, -1
	s_add_i32 s51, 0, 0x10000
	s_cmp_eq_u32 s50, 28
	s_cselect_b32 s35, s2, s31
	s_cselect_b32 s34, s3, s30
	s_cselect_b32 s31, s19, s49
	s_cselect_b32 s30, s21, s48
	s_add_i32 s54, 0, 0x14000
	v_add_u32_e32 v142, s51, v181
	v_add_u32_e32 v158, s54, v181
	ds_read_b128 v[130:133], v142
	ds_read_b128 v[134:137], v142 offset:1024
	ds_read_b128 v[138:141], v142 offset:2048
	ds_read_b128 v[142:145], v142 offset:3072
	ds_read_b128 v[146:149], v158
	ds_read_b128 v[150:153], v158 offset:1024
	ds_read_b128 v[154:157], v158 offset:2048
	ds_read_b128 v[158:161], v158 offset:3072
	v_lshl_add_u64 v[172:173], s[26:27], 0, v[168:169]
	s_add_i32 m0, s41, 0xc000
	ds_read_b128 v[176:179], v195
	ds_read_b128 v[182:185], v195 offset:1024
	ds_read_b128 v[190:193], v195 offset:2048
	ds_read_b128 v[196:199], v195 offset:3072
	ds_read_b128 v[200:203], v195 offset:4096
	ds_read_b128 v[204:207], v195 offset:5120
	ds_read_b128 v[216:219], v195 offset:6144
	ds_read_b128 v[220:223], v195 offset:7168
	global_load_lds_dwordx4 v[172:173], off
	v_lshl_add_u64 v[172:173], s[26:27], 0, v[170:171]
	s_add_i32 m0, s41, 0xe000
	s_nop 0
	global_load_lds_dwordx4 v[172:173], off
	s_setprio 1
	s_waitcnt vmcnt(8) lgkmcnt(0)
	s_barrier
	v_mfma_f32_16x16x32_bf16 v[126:129], v[130:133], v[176:179], v[126:129]
	v_mfma_f32_16x16x32_bf16 v[122:125], v[138:141], v[176:179], v[122:125]
	v_mfma_f32_16x16x32_bf16 v[110:113], v[130:133], v[190:193], v[110:113]
	v_mfma_f32_16x16x32_bf16 v[106:109], v[138:141], v[190:193], v[106:109]
	v_mfma_f32_16x16x32_bf16 v[94:97], v[130:133], v[200:203], v[94:97]
	v_mfma_f32_16x16x32_bf16 v[90:93], v[138:141], v[200:203], v[90:93]
	v_mfma_f32_16x16x32_bf16 v[78:81], v[130:133], v[216:219], v[78:81]
	v_mfma_f32_16x16x32_bf16 v[74:77], v[138:141], v[216:219], v[74:77]
	v_mfma_f32_16x16x32_bf16 v[126:129], v[134:137], v[182:185], v[126:129]
	v_mfma_f32_16x16x32_bf16 v[122:125], v[142:145], v[182:185], v[122:125]
	v_mfma_f32_16x16x32_bf16 v[110:113], v[134:137], v[196:199], v[110:113]
	v_mfma_f32_16x16x32_bf16 v[106:109], v[142:145], v[196:199], v[106:109]
	v_mfma_f32_16x16x32_bf16 v[94:97], v[134:137], v[204:207], v[94:97]
	v_mfma_f32_16x16x32_bf16 v[90:93], v[142:145], v[204:207], v[90:93]
	v_mfma_f32_16x16x32_bf16 v[78:81], v[134:137], v[220:223], v[78:81]
	v_mfma_f32_16x16x32_bf16 v[74:77], v[142:145], v[220:223], v[74:77]
	v_mfma_f32_16x16x32_bf16 v[118:121], v[146:149], v[176:179], v[118:121]
	v_mfma_f32_16x16x32_bf16 v[114:117], v[154:157], v[176:179], v[114:117]
	v_mfma_f32_16x16x32_bf16 v[102:105], v[146:149], v[190:193], v[102:105]
	v_mfma_f32_16x16x32_bf16 v[98:101], v[154:157], v[190:193], v[98:101]
	v_mfma_f32_16x16x32_bf16 v[86:89], v[146:149], v[200:203], v[86:89]
	v_mfma_f32_16x16x32_bf16 v[82:85], v[154:157], v[200:203], v[82:85]
	v_mfma_f32_16x16x32_bf16 v[70:73], v[146:149], v[216:219], v[70:73]
	v_mfma_f32_16x16x32_bf16 v[66:69], v[154:157], v[216:219], v[66:69]
	v_mfma_f32_16x16x32_bf16 v[118:121], v[150:153], v[182:185], v[118:121]
	v_mfma_f32_16x16x32_bf16 v[114:117], v[158:161], v[182:185], v[114:117]
	v_mfma_f32_16x16x32_bf16 v[102:105], v[150:153], v[196:199], v[102:105]
	v_mfma_f32_16x16x32_bf16 v[98:101], v[158:161], v[196:199], v[98:101]
	v_mfma_f32_16x16x32_bf16 v[86:89], v[150:153], v[204:207], v[86:89]
	v_mfma_f32_16x16x32_bf16 v[82:85], v[158:161], v[204:207], v[82:85]
	v_mfma_f32_16x16x32_bf16 v[70:73], v[150:153], v[220:223], v[70:73]
	v_mfma_f32_16x16x32_bf16 v[66:69], v[158:161], v[220:223], v[66:69]
	s_setprio 0
	s_barrier
	s_add_i32 s51, s51, s40
	v_lshl_add_u64 v[172:173], s[30:31], 0, v[210:211]
	s_mov_b32 m0, s51
	ds_read_b128 v[176:179], v195 offset:16384
	ds_read_b128 v[182:185], v195 offset:17408
	ds_read_b128 v[190:193], v195 offset:18432
	ds_read_b128 v[196:199], v195 offset:19456
	ds_read_b128 v[200:203], v195 offset:20480
	ds_read_b128 v[204:207], v195 offset:21504
	ds_read_b128 v[216:219], v195 offset:22528
	ds_read_b128 v[220:223], v195 offset:23552
	global_load_lds_dwordx4 v[172:173], off
	s_add_i32 m0, s51, 0x2000
	s_add_u32 s52, s30, 0x80000
	v_lshl_add_u64 v[186:187], s[30:31], 0, v[162:163]
	s_addc_u32 s53, s31, 0
	s_add_i32 s51, s54, s40
	global_load_lds_dwordx4 v[186:187], off
	v_lshl_add_u64 v[208:209], s[52:53], 0, v[210:211]
	s_mov_b32 m0, s51
	v_lshl_add_u64 v[212:213], s[34:35], 0, v[164:165]
	global_load_lds_dwordx4 v[208:209], off
	v_lshl_add_u64 v[208:209], s[52:53], 0, v[162:163]
	s_add_i32 m0, s51, 0x2000
	s_nop 0
	global_load_lds_dwordx4 v[208:209], off
	v_lshl_add_u64 v[208:209], s[34:35], 0, v[166:167]
	s_mov_b32 m0, s41
	s_nop 0
	global_load_lds_dwordx4 v[208:209], off
	s_mov_b32 m0, s42
	s_nop 0
	global_load_lds_dwordx4 v[212:213], off
	s_setprio 1
	s_waitcnt vmcnt(8) lgkmcnt(0)
	s_barrier
	v_mfma_f32_16x16x32_bf16 v[62:65], v[130:133], v[176:179], v[62:65]
	v_mfma_f32_16x16x32_bf16 v[58:61], v[138:141], v[176:179], v[58:61]
	v_mfma_f32_16x16x32_bf16 v[46:49], v[130:133], v[190:193], v[46:49]
	v_mfma_f32_16x16x32_bf16 v[42:45], v[138:141], v[190:193], v[42:45]
	v_mfma_f32_16x16x32_bf16 v[30:33], v[130:133], v[200:203], v[30:33]
	v_mfma_f32_16x16x32_bf16 v[26:29], v[138:141], v[200:203], v[26:29]
	v_mfma_f32_16x16x32_bf16 v[14:17], v[130:133], v[216:219], v[14:17]
	v_mfma_f32_16x16x32_bf16 v[10:13], v[138:141], v[216:219], v[10:13]
	v_mfma_f32_16x16x32_bf16 v[62:65], v[134:137], v[182:185], v[62:65]
	v_mfma_f32_16x16x32_bf16 v[58:61], v[142:145], v[182:185], v[58:61]
	v_mfma_f32_16x16x32_bf16 v[46:49], v[134:137], v[196:199], v[46:49]
	v_mfma_f32_16x16x32_bf16 v[42:45], v[142:145], v[196:199], v[42:45]
	v_mfma_f32_16x16x32_bf16 v[30:33], v[134:137], v[204:207], v[30:33]
	v_mfma_f32_16x16x32_bf16 v[26:29], v[142:145], v[204:207], v[26:29]
	v_mfma_f32_16x16x32_bf16 v[14:17], v[134:137], v[220:223], v[14:17]
	v_mfma_f32_16x16x32_bf16 v[10:13], v[142:145], v[220:223], v[10:13]
	v_mfma_f32_16x16x32_bf16 v[54:57], v[146:149], v[176:179], v[54:57]
	v_mfma_f32_16x16x32_bf16 v[50:53], v[154:157], v[176:179], v[50:53]
	v_mfma_f32_16x16x32_bf16 v[38:41], v[146:149], v[190:193], v[38:41]
	v_mfma_f32_16x16x32_bf16 v[34:37], v[154:157], v[190:193], v[34:37]
	v_mfma_f32_16x16x32_bf16 v[22:25], v[146:149], v[200:203], v[22:25]
	v_mfma_f32_16x16x32_bf16 v[18:21], v[154:157], v[200:203], v[18:21]
	v_mfma_f32_16x16x32_bf16 v[6:9], v[146:149], v[216:219], v[6:9]
	v_mfma_f32_16x16x32_bf16 v[2:5], v[154:157], v[216:219], v[2:5]
	v_mfma_f32_16x16x32_bf16 v[54:57], v[150:153], v[182:185], v[54:57]
	v_mfma_f32_16x16x32_bf16 v[50:53], v[158:161], v[182:185], v[50:53]
	v_mfma_f32_16x16x32_bf16 v[38:41], v[150:153], v[196:199], v[38:41]
	v_mfma_f32_16x16x32_bf16 v[34:37], v[158:161], v[196:199], v[34:37]
	v_mfma_f32_16x16x32_bf16 v[22:25], v[150:153], v[204:207], v[22:25]
	v_mfma_f32_16x16x32_bf16 v[18:21], v[158:161], v[204:207], v[18:21]
	v_mfma_f32_16x16x32_bf16 v[6:9], v[150:153], v[220:223], v[6:9]
	v_mfma_f32_16x16x32_bf16 v[2:5], v[158:161], v[220:223], v[2:5]
	s_setprio 0
	s_barrier
	s_add_i32 s51, 0, 0x18000
	s_add_i32 s52, 0, 0x1c000
	v_add_u32_e32 v142, s51, v181
	v_add_u32_e32 v158, s52, v181
	ds_read_b128 v[130:133], v142
	ds_read_b128 v[134:137], v142 offset:1024
	ds_read_b128 v[138:141], v142 offset:2048
	ds_read_b128 v[142:145], v142 offset:3072
	ds_read_b128 v[146:149], v158
	ds_read_b128 v[150:153], v158 offset:1024
	ds_read_b128 v[154:157], v158 offset:2048
	ds_read_b128 v[158:161], v158 offset:3072
	s_add_u32 s34, s34, 0x80000
	s_addc_u32 s35, s35, 0
	s_mov_b32 m0, s43
	v_lshl_add_u64 v[214:215], s[34:35], 0, v[166:167]
	ds_read_b128 v[176:179], v195 offset:32768
	ds_read_b128 v[182:185], v195 offset:33792
	ds_read_b128 v[190:193], v195 offset:34816
	ds_read_b128 v[196:199], v195 offset:35840
	ds_read_b128 v[200:203], v195 offset:36864
	ds_read_b128 v[204:207], v195 offset:37888
	ds_read_b128 v[216:219], v195 offset:38912
	ds_read_b128 v[220:223], v195 offset:39936
	global_load_lds_dwordx4 v[214:215], off
	v_lshl_add_u64 v[214:215], s[34:35], 0, v[164:165]
	s_mov_b32 m0, s44
	s_nop 0
	global_load_lds_dwordx4 v[214:215], off
	s_setprio 1
	s_waitcnt vmcnt(8) lgkmcnt(0)
	s_barrier
	v_mfma_f32_16x16x32_bf16 v[126:129], v[130:133], v[176:179], v[126:129]
	v_mfma_f32_16x16x32_bf16 v[122:125], v[138:141], v[176:179], v[122:125]
	v_mfma_f32_16x16x32_bf16 v[110:113], v[130:133], v[190:193], v[110:113]
	v_mfma_f32_16x16x32_bf16 v[106:109], v[138:141], v[190:193], v[106:109]
	v_mfma_f32_16x16x32_bf16 v[94:97], v[130:133], v[200:203], v[94:97]
	v_mfma_f32_16x16x32_bf16 v[90:93], v[138:141], v[200:203], v[90:93]
	v_mfma_f32_16x16x32_bf16 v[78:81], v[130:133], v[216:219], v[78:81]
	v_mfma_f32_16x16x32_bf16 v[74:77], v[138:141], v[216:219], v[74:77]
	v_mfma_f32_16x16x32_bf16 v[126:129], v[134:137], v[182:185], v[126:129]
	v_mfma_f32_16x16x32_bf16 v[122:125], v[142:145], v[182:185], v[122:125]
	v_mfma_f32_16x16x32_bf16 v[110:113], v[134:137], v[196:199], v[110:113]
	v_mfma_f32_16x16x32_bf16 v[106:109], v[142:145], v[196:199], v[106:109]
	v_mfma_f32_16x16x32_bf16 v[94:97], v[134:137], v[204:207], v[94:97]
	v_mfma_f32_16x16x32_bf16 v[90:93], v[142:145], v[204:207], v[90:93]
	v_mfma_f32_16x16x32_bf16 v[78:81], v[134:137], v[220:223], v[78:81]
	v_mfma_f32_16x16x32_bf16 v[74:77], v[142:145], v[220:223], v[74:77]
	v_mfma_f32_16x16x32_bf16 v[118:121], v[146:149], v[176:179], v[118:121]
	v_mfma_f32_16x16x32_bf16 v[114:117], v[154:157], v[176:179], v[114:117]
	v_mfma_f32_16x16x32_bf16 v[102:105], v[146:149], v[190:193], v[102:105]
	v_mfma_f32_16x16x32_bf16 v[98:101], v[154:157], v[190:193], v[98:101]
	v_mfma_f32_16x16x32_bf16 v[86:89], v[146:149], v[200:203], v[86:89]
	v_mfma_f32_16x16x32_bf16 v[82:85], v[154:157], v[200:203], v[82:85]
	v_mfma_f32_16x16x32_bf16 v[70:73], v[146:149], v[216:219], v[70:73]
	v_mfma_f32_16x16x32_bf16 v[66:69], v[154:157], v[216:219], v[66:69]
	v_mfma_f32_16x16x32_bf16 v[118:121], v[150:153], v[182:185], v[118:121]
	v_mfma_f32_16x16x32_bf16 v[114:117], v[158:161], v[182:185], v[114:117]
	v_mfma_f32_16x16x32_bf16 v[102:105], v[150:153], v[196:199], v[102:105]
	v_mfma_f32_16x16x32_bf16 v[98:101], v[158:161], v[196:199], v[98:101]
	v_mfma_f32_16x16x32_bf16 v[86:89], v[150:153], v[204:207], v[86:89]
	v_mfma_f32_16x16x32_bf16 v[82:85], v[158:161], v[204:207], v[82:85]
	v_mfma_f32_16x16x32_bf16 v[70:73], v[150:153], v[220:223], v[70:73]
	v_mfma_f32_16x16x32_bf16 v[66:69], v[158:161], v[220:223], v[66:69]
	s_setprio 0
	s_barrier
	s_add_i32 s34, s51, s40
	v_lshl_add_u64 v[172:173], v[172:173], 0, s[64:65]
	s_mov_b32 m0, s34
	ds_read_b128 v[176:179], v195 offset:49152
	ds_read_b128 v[182:185], v195 offset:50176
	ds_read_b128 v[190:193], v195 offset:51200
	ds_read_b128 v[196:199], v195 offset:52224
	ds_read_b128 v[200:203], v195 offset:53248
	ds_read_b128 v[204:207], v195 offset:54272
	ds_read_b128 v[216:219], v195 offset:55296
	ds_read_b128 v[220:223], v195 offset:56320
	global_load_lds_dwordx4 v[172:173], off
	s_add_i32 m0, s34, 0x2000
	s_add_u32 s30, s30, 0x80080
	v_lshl_add_u64 v[172:173], v[186:187], 0, s[64:65]
	s_addc_u32 s31, s31, 0
	s_add_i32 s34, s52, s40
	global_load_lds_dwordx4 v[172:173], off
	v_lshl_add_u64 v[172:173], s[30:31], 0, v[210:211]
	s_mov_b32 m0, s34
	s_nop 0
	global_load_lds_dwordx4 v[172:173], off
	v_lshl_add_u64 v[172:173], s[30:31], 0, v[162:163]
	s_add_i32 m0, s34, 0x2000
	s_nop 0
	global_load_lds_dwordx4 v[172:173], off
	v_lshl_add_u64 v[172:173], v[208:209], 0, s[64:65]
	s_mov_b32 m0, s45
	s_nop 0
	global_load_lds_dwordx4 v[172:173], off
	v_lshl_add_u64 v[172:173], v[212:213], 0, s[64:65]
	s_mov_b32 m0, s46
	s_nop 0
	global_load_lds_dwordx4 v[172:173], off
	s_setprio 1
	s_waitcnt vmcnt(8) lgkmcnt(0)
	s_barrier
	v_mfma_f32_16x16x32_bf16 v[62:65], v[130:133], v[176:179], v[62:65]
	v_mfma_f32_16x16x32_bf16 v[58:61], v[138:141], v[176:179], v[58:61]
	v_mfma_f32_16x16x32_bf16 v[46:49], v[130:133], v[190:193], v[46:49]
	v_mfma_f32_16x16x32_bf16 v[42:45], v[138:141], v[190:193], v[42:45]
	v_mfma_f32_16x16x32_bf16 v[30:33], v[130:133], v[200:203], v[30:33]
	v_mfma_f32_16x16x32_bf16 v[26:29], v[138:141], v[200:203], v[26:29]
	v_mfma_f32_16x16x32_bf16 v[14:17], v[130:133], v[216:219], v[14:17]
	v_mfma_f32_16x16x32_bf16 v[10:13], v[138:141], v[216:219], v[10:13]
	v_mfma_f32_16x16x32_bf16 v[62:65], v[134:137], v[182:185], v[62:65]
	v_mfma_f32_16x16x32_bf16 v[58:61], v[142:145], v[182:185], v[58:61]
	v_mfma_f32_16x16x32_bf16 v[46:49], v[134:137], v[196:199], v[46:49]
	v_mfma_f32_16x16x32_bf16 v[42:45], v[142:145], v[196:199], v[42:45]
	v_mfma_f32_16x16x32_bf16 v[30:33], v[134:137], v[204:207], v[30:33]
	v_mfma_f32_16x16x32_bf16 v[26:29], v[142:145], v[204:207], v[26:29]
	v_mfma_f32_16x16x32_bf16 v[14:17], v[134:137], v[220:223], v[14:17]
	v_mfma_f32_16x16x32_bf16 v[10:13], v[142:145], v[220:223], v[10:13]
	v_mfma_f32_16x16x32_bf16 v[54:57], v[146:149], v[176:179], v[54:57]
	v_mfma_f32_16x16x32_bf16 v[50:53], v[154:157], v[176:179], v[50:53]
	v_mfma_f32_16x16x32_bf16 v[38:41], v[146:149], v[190:193], v[38:41]
	v_mfma_f32_16x16x32_bf16 v[34:37], v[154:157], v[190:193], v[34:37]
	v_mfma_f32_16x16x32_bf16 v[22:25], v[146:149], v[200:203], v[22:25]
	v_mfma_f32_16x16x32_bf16 v[18:21], v[154:157], v[200:203], v[18:21]
	v_mfma_f32_16x16x32_bf16 v[6:9], v[146:149], v[216:219], v[6:9]
	v_mfma_f32_16x16x32_bf16 v[2:5], v[154:157], v[216:219], v[2:5]
	v_mfma_f32_16x16x32_bf16 v[54:57], v[150:153], v[182:185], v[54:57]
	v_mfma_f32_16x16x32_bf16 v[50:53], v[158:161], v[182:185], v[50:53]
	v_mfma_f32_16x16x32_bf16 v[38:41], v[150:153], v[196:199], v[38:41]
	v_mfma_f32_16x16x32_bf16 v[34:37], v[158:161], v[196:199], v[34:37]
	v_mfma_f32_16x16x32_bf16 v[22:25], v[150:153], v[204:207], v[22:25]
	v_mfma_f32_16x16x32_bf16 v[18:21], v[158:161], v[204:207], v[18:21]
	v_mfma_f32_16x16x32_bf16 v[6:9], v[150:153], v[220:223], v[6:9]
	v_mfma_f32_16x16x32_bf16 v[2:5], v[158:161], v[220:223], v[2:5]
	s_setprio 0
	s_barrier
	s_add_i32 s50, s50, 2
	s_add_u32 s26, s26, 0x100
	s_addc_u32 s27, s27, 0
	s_add_u32 s48, s48, 0x100
	s_addc_u32 s49, s49, 0
	s_cmp_gt_u32 s50, 29
	s_cbranch_scc0 .LBB0_1091
	v_readlane_b32 s50, v254, 38
	s_and_b64 vcc, exec, s[16:17]
	v_readlane_b32 s51, v254, 39
	s_cbranch_vccz .LBB0_1094
	s_barrier

.LBB0_1180:
	s_add_u32 s36, s34, 0x100
	s_addc_u32 s37, s35, 0
	s_add_i32 s57, 0, 0x10000
	s_cmpk_eq_i32 s56, 0x7c
	s_cselect_b32 s41, s2, s37
	s_cselect_b32 s40, s3, s36
	s_cselect_b32 s39, s23, s55
	s_cselect_b32 s38, s25, s54
	s_add_i32 s58, 0, 0x14000
	v_add_u32_e32 v78, s57, v233
	v_add_u32_e32 v98, s58, v233
	ds_read_b128 v[66:69], v78
	ds_read_b128 v[70:73], v78 offset:1024
	ds_read_b128 v[74:77], v78 offset:2048
	ds_read_b128 v[78:81], v78 offset:3072
	ds_read_b128 v[82:85], v98
	ds_read_b128 v[86:89], v98 offset:1024
	ds_read_b128 v[94:97], v98 offset:2048
	ds_read_b128 v[98:101], v98 offset:3072
	v_lshl_add_u64 v[200:201], s[34:35], 0, v[196:197]
	s_add_i32 m0, s47, 0xc000
	ds_read_b128 v[162:165], v235
	ds_read_b128 v[166:169], v235 offset:1024
	ds_read_b128 v[170:173], v235 offset:2048
	ds_read_b128 v[174:177], v235 offset:3072
	ds_read_b128 v[178:181], v235 offset:4096
	ds_read_b128 v[182:185], v235 offset:5120
	ds_read_b128 v[186:189], v235 offset:6144
	ds_read_b128 v[190:193], v235 offset:7168
	global_load_lds_dwordx4 v[200:201], off
	v_lshl_add_u64 v[200:201], s[34:35], 0, v[198:199]
	s_add_i32 m0, s47, 0xe000
	s_nop 0
	global_load_lds_dwordx4 v[200:201], off
	s_setprio 1
	s_waitcnt vmcnt(8) lgkmcnt(0)
	s_barrier
	v_mfma_f32_16x16x32_bf16 v[158:161], v[66:69], v[162:165], v[158:161]
	v_mfma_f32_16x16x32_bf16 v[154:157], v[74:77], v[162:165], v[154:157]
	v_mfma_f32_16x16x32_bf16 v[142:145], v[66:69], v[170:173], v[142:145]
	v_mfma_f32_16x16x32_bf16 v[138:141], v[74:77], v[170:173], v[138:141]
	v_mfma_f32_16x16x32_bf16 v[126:129], v[66:69], v[178:181], v[126:129]
	v_mfma_f32_16x16x32_bf16 v[122:125], v[74:77], v[178:181], v[122:125]
	v_mfma_f32_16x16x32_bf16 v[110:113], v[66:69], v[186:189], v[110:113]
	v_mfma_f32_16x16x32_bf16 v[106:109], v[74:77], v[186:189], v[106:109]
	v_mfma_f32_16x16x32_bf16 v[158:161], v[70:73], v[166:169], v[158:161]
	v_mfma_f32_16x16x32_bf16 v[154:157], v[78:81], v[166:169], v[154:157]
	v_mfma_f32_16x16x32_bf16 v[142:145], v[70:73], v[174:177], v[142:145]
	v_mfma_f32_16x16x32_bf16 v[138:141], v[78:81], v[174:177], v[138:141]
	v_mfma_f32_16x16x32_bf16 v[126:129], v[70:73], v[182:185], v[126:129]
	v_mfma_f32_16x16x32_bf16 v[122:125], v[78:81], v[182:185], v[122:125]
	v_mfma_f32_16x16x32_bf16 v[110:113], v[70:73], v[190:193], v[110:113]
	v_mfma_f32_16x16x32_bf16 v[106:109], v[78:81], v[190:193], v[106:109]
	v_mfma_f32_16x16x32_bf16 v[150:153], v[82:85], v[162:165], v[150:153]
	v_mfma_f32_16x16x32_bf16 v[146:149], v[94:97], v[162:165], v[146:149]
	v_mfma_f32_16x16x32_bf16 v[134:137], v[82:85], v[170:173], v[134:137]
	v_mfma_f32_16x16x32_bf16 v[130:133], v[94:97], v[170:173], v[130:133]
	v_mfma_f32_16x16x32_bf16 v[118:121], v[82:85], v[178:181], v[118:121]
	v_mfma_f32_16x16x32_bf16 v[114:117], v[94:97], v[178:181], v[114:117]
	v_mfma_f32_16x16x32_bf16 v[102:105], v[82:85], v[186:189], v[102:105]
	v_mfma_f32_16x16x32_bf16 v[90:93], v[94:97], v[186:189], v[90:93]
	v_mfma_f32_16x16x32_bf16 v[150:153], v[86:89], v[166:169], v[150:153]
	v_mfma_f32_16x16x32_bf16 v[146:149], v[98:101], v[166:169], v[146:149]
	v_mfma_f32_16x16x32_bf16 v[134:137], v[86:89], v[174:177], v[134:137]
	v_mfma_f32_16x16x32_bf16 v[130:133], v[98:101], v[174:177], v[130:133]
	v_mfma_f32_16x16x32_bf16 v[118:121], v[86:89], v[182:185], v[118:121]
	v_mfma_f32_16x16x32_bf16 v[114:117], v[98:101], v[182:185], v[114:117]
	v_mfma_f32_16x16x32_bf16 v[102:105], v[86:89], v[190:193], v[102:105]
	v_mfma_f32_16x16x32_bf16 v[90:93], v[98:101], v[190:193], v[90:93]
	s_setprio 0
	s_barrier
	s_add_i32 s34, s57, s46
	v_lshl_add_u64 v[200:201], s[38:39], 0, v[210:211]
	s_mov_b32 m0, s34
	ds_read_b128 v[162:165], v235 offset:16384
	ds_read_b128 v[166:169], v235 offset:17408
	ds_read_b128 v[170:173], v235 offset:18432
	ds_read_b128 v[174:177], v235 offset:19456
	ds_read_b128 v[178:181], v235 offset:20480
	ds_read_b128 v[182:185], v235 offset:21504
	ds_read_b128 v[186:189], v235 offset:22528
	ds_read_b128 v[190:193], v235 offset:23552
	global_load_lds_dwordx4 v[200:201], off
	s_add_i32 m0, s34, 0x2000
	s_add_u32 s34, s38, 0x200000
	v_lshl_add_u64 v[202:203], s[38:39], 0, v[194:195]
	s_addc_u32 s35, s39, 0
	s_add_i32 s57, s58, s46
	global_load_lds_dwordx4 v[202:203], off
	v_lshl_add_u64 v[204:205], s[34:35], 0, v[210:211]
	s_mov_b32 m0, s57
	v_lshl_add_u64 v[206:207], s[40:41], 0, v[194:195]
	global_load_lds_dwordx4 v[204:205], off
	v_lshl_add_u64 v[204:205], s[34:35], 0, v[194:195]
	s_add_i32 m0, s57, 0x2000
	s_nop 0
	global_load_lds_dwordx4 v[204:205], off
	v_lshl_add_u64 v[204:205], s[40:41], 0, v[210:211]
	s_mov_b32 m0, s47
	s_nop 0
	global_load_lds_dwordx4 v[204:205], off
	s_mov_b32 m0, s48
	s_nop 0
	global_load_lds_dwordx4 v[206:207], off
	s_setprio 1
	s_waitcnt vmcnt(8) lgkmcnt(0)
	s_barrier
	v_mfma_f32_16x16x32_bf16 v[62:65], v[66:69], v[162:165], v[62:65]
	v_mfma_f32_16x16x32_bf16 v[58:61], v[74:77], v[162:165], v[58:61]
	v_mfma_f32_16x16x32_bf16 v[46:49], v[66:69], v[170:173], v[46:49]
	v_mfma_f32_16x16x32_bf16 v[42:45], v[74:77], v[170:173], v[42:45]
	v_mfma_f32_16x16x32_bf16 v[30:33], v[66:69], v[178:181], v[30:33]
	v_mfma_f32_16x16x32_bf16 v[26:29], v[74:77], v[178:181], v[26:29]
	v_mfma_f32_16x16x32_bf16 v[14:17], v[66:69], v[186:189], v[14:17]
	v_mfma_f32_16x16x32_bf16 v[10:13], v[74:77], v[186:189], v[10:13]
	v_mfma_f32_16x16x32_bf16 v[62:65], v[70:73], v[166:169], v[62:65]
	v_mfma_f32_16x16x32_bf16 v[58:61], v[78:81], v[166:169], v[58:61]
	v_mfma_f32_16x16x32_bf16 v[46:49], v[70:73], v[174:177], v[46:49]
	v_mfma_f32_16x16x32_bf16 v[42:45], v[78:81], v[174:177], v[42:45]
	v_mfma_f32_16x16x32_bf16 v[30:33], v[70:73], v[182:185], v[30:33]
	v_mfma_f32_16x16x32_bf16 v[26:29], v[78:81], v[182:185], v[26:29]
	v_mfma_f32_16x16x32_bf16 v[14:17], v[70:73], v[190:193], v[14:17]
	v_mfma_f32_16x16x32_bf16 v[10:13], v[78:81], v[190:193], v[10:13]
	v_mfma_f32_16x16x32_bf16 v[54:57], v[82:85], v[162:165], v[54:57]
	v_mfma_f32_16x16x32_bf16 v[50:53], v[94:97], v[162:165], v[50:53]
	v_mfma_f32_16x16x32_bf16 v[38:41], v[82:85], v[170:173], v[38:41]
	v_mfma_f32_16x16x32_bf16 v[34:37], v[94:97], v[170:173], v[34:37]
	v_mfma_f32_16x16x32_bf16 v[22:25], v[82:85], v[178:181], v[22:25]
	v_mfma_f32_16x16x32_bf16 v[18:21], v[94:97], v[178:181], v[18:21]
	v_mfma_f32_16x16x32_bf16 v[6:9], v[82:85], v[186:189], v[6:9]
	v_mfma_f32_16x16x32_bf16 v[2:5], v[94:97], v[186:189], v[2:5]
	v_mfma_f32_16x16x32_bf16 v[54:57], v[86:89], v[166:169], v[54:57]
	v_mfma_f32_16x16x32_bf16 v[50:53], v[98:101], v[166:169], v[50:53]
	v_mfma_f32_16x16x32_bf16 v[38:41], v[86:89], v[174:177], v[38:41]
	v_mfma_f32_16x16x32_bf16 v[34:37], v[98:101], v[174:177], v[34:37]
	v_mfma_f32_16x16x32_bf16 v[22:25], v[86:89], v[182:185], v[22:25]
	v_mfma_f32_16x16x32_bf16 v[18:21], v[98:101], v[182:185], v[18:21]
	v_mfma_f32_16x16x32_bf16 v[6:9], v[86:89], v[190:193], v[6:9]
	v_mfma_f32_16x16x32_bf16 v[2:5], v[98:101], v[190:193], v[2:5]
	s_setprio 0
	s_barrier
	s_add_i32 s57, 0, 0x18000
	s_add_i32 s58, 0, 0x1c000
	v_add_u32_e32 v78, s57, v233
	v_add_u32_e32 v98, s58, v233
	ds_read_b128 v[66:69], v78
	ds_read_b128 v[70:73], v78 offset:1024
	ds_read_b128 v[74:77], v78 offset:2048
	ds_read_b128 v[78:81], v78 offset:3072
	ds_read_b128 v[82:85], v98
	ds_read_b128 v[86:89], v98 offset:1024
	ds_read_b128 v[94:97], v98 offset:2048
	ds_read_b128 v[98:101], v98 offset:3072
	s_add_u32 s34, s40, 0x200000
	s_addc_u32 s35, s41, 0
	s_mov_b32 m0, s49
	v_lshl_add_u64 v[208:209], s[34:35], 0, v[210:211]
	ds_read_b128 v[162:165], v235 offset:32768
	ds_read_b128 v[166:169], v235 offset:33792
	ds_read_b128 v[170:173], v235 offset:34816
	ds_read_b128 v[174:177], v235 offset:35840
	ds_read_b128 v[178:181], v235 offset:36864
	ds_read_b128 v[182:185], v235 offset:37888
	ds_read_b128 v[186:189], v235 offset:38912
	ds_read_b128 v[190:193], v235 offset:39936
	global_load_lds_dwordx4 v[208:209], off
	v_lshl_add_u64 v[208:209], s[34:35], 0, v[194:195]
	s_mov_b32 m0, s50
	s_nop 0
	global_load_lds_dwordx4 v[208:209], off
	s_setprio 1
	s_waitcnt vmcnt(8) lgkmcnt(0)
	s_barrier
	v_mfma_f32_16x16x32_bf16 v[158:161], v[66:69], v[162:165], v[158:161]
	v_mfma_f32_16x16x32_bf16 v[154:157], v[74:77], v[162:165], v[154:157]
	v_mfma_f32_16x16x32_bf16 v[142:145], v[66:69], v[170:173], v[142:145]
	v_mfma_f32_16x16x32_bf16 v[138:141], v[74:77], v[170:173], v[138:141]
	v_mfma_f32_16x16x32_bf16 v[126:129], v[66:69], v[178:181], v[126:129]
	v_mfma_f32_16x16x32_bf16 v[122:125], v[74:77], v[178:181], v[122:125]
	v_mfma_f32_16x16x32_bf16 v[110:113], v[66:69], v[186:189], v[110:113]
	v_mfma_f32_16x16x32_bf16 v[106:109], v[74:77], v[186:189], v[106:109]
	v_mfma_f32_16x16x32_bf16 v[158:161], v[70:73], v[166:169], v[158:161]
	v_mfma_f32_16x16x32_bf16 v[154:157], v[78:81], v[166:169], v[154:157]
	v_mfma_f32_16x16x32_bf16 v[142:145], v[70:73], v[174:177], v[142:145]
	v_mfma_f32_16x16x32_bf16 v[138:141], v[78:81], v[174:177], v[138:141]
	v_mfma_f32_16x16x32_bf16 v[126:129], v[70:73], v[182:185], v[126:129]
	v_mfma_f32_16x16x32_bf16 v[122:125], v[78:81], v[182:185], v[122:125]
	v_mfma_f32_16x16x32_bf16 v[110:113], v[70:73], v[190:193], v[110:113]
	v_mfma_f32_16x16x32_bf16 v[106:109], v[78:81], v[190:193], v[106:109]
	v_mfma_f32_16x16x32_bf16 v[150:153], v[82:85], v[162:165], v[150:153]
	v_mfma_f32_16x16x32_bf16 v[146:149], v[94:97], v[162:165], v[146:149]
	v_mfma_f32_16x16x32_bf16 v[134:137], v[82:85], v[170:173], v[134:137]
	v_mfma_f32_16x16x32_bf16 v[130:133], v[94:97], v[170:173], v[130:133]
	v_mfma_f32_16x16x32_bf16 v[118:121], v[82:85], v[178:181], v[118:121]
	v_mfma_f32_16x16x32_bf16 v[114:117], v[94:97], v[178:181], v[114:117]
	v_mfma_f32_16x16x32_bf16 v[102:105], v[82:85], v[186:189], v[102:105]
	v_mfma_f32_16x16x32_bf16 v[90:93], v[94:97], v[186:189], v[90:93]
	v_mfma_f32_16x16x32_bf16 v[150:153], v[86:89], v[166:169], v[150:153]
	v_mfma_f32_16x16x32_bf16 v[146:149], v[98:101], v[166:169], v[146:149]
	v_mfma_f32_16x16x32_bf16 v[134:137], v[86:89], v[174:177], v[134:137]
	v_mfma_f32_16x16x32_bf16 v[130:133], v[98:101], v[174:177], v[130:133]
	v_mfma_f32_16x16x32_bf16 v[118:121], v[86:89], v[182:185], v[118:121]
	v_mfma_f32_16x16x32_bf16 v[114:117], v[98:101], v[182:185], v[114:117]
	v_mfma_f32_16x16x32_bf16 v[102:105], v[86:89], v[190:193], v[102:105]
	v_mfma_f32_16x16x32_bf16 v[90:93], v[98:101], v[190:193], v[90:93]
	s_setprio 0
	s_barrier
	s_add_i32 s34, s57, s46
	v_lshl_add_u64 v[200:201], v[200:201], 0, s[64:65]
	s_mov_b32 m0, s34
	ds_read_b128 v[162:165], v235 offset:49152
	ds_read_b128 v[166:169], v235 offset:50176
	ds_read_b128 v[170:173], v235 offset:51200
	ds_read_b128 v[174:177], v235 offset:52224
	ds_read_b128 v[178:181], v235 offset:53248
	ds_read_b128 v[182:185], v235 offset:54272
	ds_read_b128 v[186:189], v235 offset:55296
	ds_read_b128 v[190:193], v235 offset:56320
	global_load_lds_dwordx4 v[200:201], off
	s_add_i32 m0, s34, 0x2000
	s_add_u32 s34, s38, 0x200080
	v_lshl_add_u64 v[200:201], v[202:203], 0, s[64:65]
	s_addc_u32 s35, s39, 0
	s_add_i32 s38, s58, s46
	global_load_lds_dwordx4 v[200:201], off
	v_lshl_add_u64 v[200:201], s[34:35], 0, v[210:211]
	s_mov_b32 m0, s38
	s_nop 0
	global_load_lds_dwordx4 v[200:201], off
	v_lshl_add_u64 v[200:201], s[34:35], 0, v[194:195]
	s_add_i32 m0, s38, 0x2000
	s_nop 0
	global_load_lds_dwordx4 v[200:201], off
	v_lshl_add_u64 v[200:201], v[204:205], 0, s[64:65]
	s_mov_b32 m0, s51
	s_nop 0
	global_load_lds_dwordx4 v[200:201], off
	v_lshl_add_u64 v[200:201], v[206:207], 0, s[64:65]
	s_mov_b32 m0, s52
	s_nop 0
	global_load_lds_dwordx4 v[200:201], off
	s_setprio 1
	s_waitcnt vmcnt(8) lgkmcnt(0)
	s_barrier
	v_mfma_f32_16x16x32_bf16 v[62:65], v[66:69], v[162:165], v[62:65]
	v_mfma_f32_16x16x32_bf16 v[58:61], v[74:77], v[162:165], v[58:61]
	v_mfma_f32_16x16x32_bf16 v[46:49], v[66:69], v[170:173], v[46:49]
	v_mfma_f32_16x16x32_bf16 v[42:45], v[74:77], v[170:173], v[42:45]
	v_mfma_f32_16x16x32_bf16 v[30:33], v[66:69], v[178:181], v[30:33]
	v_mfma_f32_16x16x32_bf16 v[26:29], v[74:77], v[178:181], v[26:29]
	v_mfma_f32_16x16x32_bf16 v[14:17], v[66:69], v[186:189], v[14:17]
	v_mfma_f32_16x16x32_bf16 v[10:13], v[74:77], v[186:189], v[10:13]
	v_mfma_f32_16x16x32_bf16 v[62:65], v[70:73], v[166:169], v[62:65]
	v_mfma_f32_16x16x32_bf16 v[58:61], v[78:81], v[166:169], v[58:61]
	v_mfma_f32_16x16x32_bf16 v[46:49], v[70:73], v[174:177], v[46:49]
	v_mfma_f32_16x16x32_bf16 v[42:45], v[78:81], v[174:177], v[42:45]
	v_mfma_f32_16x16x32_bf16 v[30:33], v[70:73], v[182:185], v[30:33]
	v_mfma_f32_16x16x32_bf16 v[26:29], v[78:81], v[182:185], v[26:29]
	v_mfma_f32_16x16x32_bf16 v[14:17], v[70:73], v[190:193], v[14:17]
	v_mfma_f32_16x16x32_bf16 v[10:13], v[78:81], v[190:193], v[10:13]
	v_mfma_f32_16x16x32_bf16 v[54:57], v[82:85], v[162:165], v[54:57]
	v_mfma_f32_16x16x32_bf16 v[50:53], v[94:97], v[162:165], v[50:53]
	v_mfma_f32_16x16x32_bf16 v[38:41], v[82:85], v[170:173], v[38:41]
	v_mfma_f32_16x16x32_bf16 v[34:37], v[94:97], v[170:173], v[34:37]
	v_mfma_f32_16x16x32_bf16 v[22:25], v[82:85], v[178:181], v[22:25]
	v_mfma_f32_16x16x32_bf16 v[18:21], v[94:97], v[178:181], v[18:21]
	v_mfma_f32_16x16x32_bf16 v[6:9], v[82:85], v[186:189], v[6:9]
	v_mfma_f32_16x16x32_bf16 v[2:5], v[94:97], v[186:189], v[2:5]
	v_mfma_f32_16x16x32_bf16 v[54:57], v[86:89], v[166:169], v[54:57]
	v_mfma_f32_16x16x32_bf16 v[50:53], v[98:101], v[166:169], v[50:53]
	v_mfma_f32_16x16x32_bf16 v[38:41], v[86:89], v[174:177], v[38:41]
	v_mfma_f32_16x16x32_bf16 v[34:37], v[98:101], v[174:177], v[34:37]
	v_mfma_f32_16x16x32_bf16 v[22:25], v[86:89], v[182:185], v[22:25]
	v_mfma_f32_16x16x32_bf16 v[18:21], v[98:101], v[182:185], v[18:21]
	v_mfma_f32_16x16x32_bf16 v[6:9], v[86:89], v[190:193], v[6:9]
	v_mfma_f32_16x16x32_bf16 v[2:5], v[98:101], v[190:193], v[2:5]
	s_setprio 0
	s_barrier
	s_add_i32 s56, s56, 2
	s_add_u32 s54, s54, 0x100
	s_addc_u32 s55, s55, 0
	s_cmpk_gt_u32 s56, 0x7d
	s_mov_b64 s[34:35], s[36:37]
	s_cbranch_scc0 .LBB0_1180
	s_and_b64 vcc, exec, s[20:21]
	s_cbranch_vccz .LBB0_1183
	s_barrier
